# GEMM K-loops: dropped per-block s_setprio flips (stacked on attention edits)
# speedup vs baseline: 1.0230x; 1.0063x over previous
; #define PG8_STAGE(bufoff, gbase, voff) do { _Pragma("unroll") for (int _i = 0; _i < 2; ++_i) \
;         __builtin_amdgcn_global_load_lds((const unsigned*)((const char*)(gbase) + (voff)[_i]), (PG8_LAS unsigned*)(lds + (bufoff) + ldsw + _i * 8192), 16, 0, 0); } while (0)
; #define PG8_LDA(dst, b, h) do { _Pragma("unroll") for (int m = 0; m < 4; ++m) _Pragma("unroll") for (int k = 0; k < 2; ++k) dst[m][k] = *(const PG8_LAS bf16x8*)(lds + PG8_SA(b, h) + aoff + m * 2048 + k * 1024); } while (0)
; #define PG8_LDB(dst, b, h) do { _Pragma("unroll") for (int n = 0; n < 2; ++n) _Pragma("unroll") for (int k = 0; k < 2; ++k) dst[n][k] = *(const PG8_LAS bf16x8*)(lds + PG8_SB(b, h) + boff + n * 2048 + k * 1024); } while (0)
; #define PG8_MMA(ai, bj, At, Bt) do { __builtin_amdgcn_s_setprio(1); _Pragma("unroll") for (int m = 0; m < 4; ++m) _Pragma("unroll") for (int n = 0; n < 2; ++n) _Pragma("unroll") for (int k = 0; k < 2; ++k) \
;         acc[ai][bj][m][n] = __builtin_amdgcn_mfma_f32_16x16x32_bf16(Bt[n][k], At[m][k], acc[ai][bj][m][n], 0, 0, 0); __builtin_amdgcn_s_setprio(0); } while (0)
; #define PG8_WAIT_V(n) asm volatile("s_waitcnt vmcnt(" #n ")" ::: "memory")
; #define PG8_BAR __builtin_amdgcn_s_barrier()
; template <class Epi, class Sched, bool ALIGN_EPI = false, bool SP2 = false>
; __device__ __forceinline__ void gemm_phase(PG8_LAS unsigned char* lds, const Gemm g, const Sched& S, const Epi& E) {
;     ...
;         for (int t = 0; t < nt; t += 2) {
;             const bool last = (t == nt - 2);
;             const char* a1 = cA + (size_t)(t + 1) * kstep;
;             const char* a2 = last ? nA : cA + (size_t)(t + 2) * kstep; const char* b2 = last ? nB : cB + (size_t)(t + 2) * kstep;
;             const char* a3 = a2 + kstep; const char* b3 = b2 + kstep;
;             if (last && has_next) S.a_ready(nxt);
;             if constexpr (SP2) {
;             PG8_LDB(B0, 0, 0); PG8_LDB(B1, 0, 1); PG8_SCHED; PG8_LDA(At, 0, 0); PG8_STAGE(PG8_SA(1, 1), a1 + hstep, voffA);
;             PG8_WAIT_V(8); PG8_WAIT_L(0); PG8_BAR; PG8_MMA(0, 0, At, B0); PG8_MMA(0, 1, At, B1); PG8_BAR; PG8_SCHED;
;             PG8_LDA(At, 0, 1); PG8_STAGE(PG8_SB(0, 0), b2, voffB); PG8_STAGE(PG8_SB(0, 1), b2 + hstep, voffB); PG8_STAGE(PG8_SA(0, 0), a2, voffA);
;             PG8_WAIT_V(8); PG8_WAIT_L(0); PG8_BAR; PG8_MMA(1, 0, At, B0); PG8_MMA(1, 1, At, B1); PG8_BAR; PG8_SCHED;
.LBB0_164:
	s_add_u32 s58, s72, 0xfffc0080
	s_addc_u32 s59, s73, -1
	s_add_i32 s84, 0, 0x10000
	s_cmp_eq_u32 s94, 12
	s_cselect_b32 s65, s36, s59
	s_cselect_b32 s64, s37, s58
	v_add_u32_e32 v140, s84, v146
	s_cselect_b32 s59, s51, s93
	s_cselect_b32 s58, s53, s92
	s_add_i32 s96, 0, 0x14000
	ds_read_b128 v[142:145], v140
	ds_read_b128 v[150:153], v140 offset:1024
	ds_read_b128 v[154:157], v140 offset:2048
	ds_read_b128 v[158:161], v140 offset:3072
	v_add_u32_e32 v140, s96, v146
	ds_read_b128 v[162:165], v140
	ds_read_b128 v[166:169], v140 offset:1024
	ds_read_b128 v[170:173], v140 offset:2048
	ds_read_b128 v[174:177], v140 offset:3072
	v_lshl_add_u64 v[186:187], s[72:73], 0, v[136:137]
	s_add_i32 m0, s19, 0xc000
	ds_read_b128 v[178:181], v148
	ds_read_b128 v[182:185], v148 offset:1024
	ds_read_b128 v[190:193], v148 offset:2048
	ds_read_b128 v[194:197], v148 offset:3072
	ds_read_b128 v[198:201], v148 offset:4096
	ds_read_b128 v[202:205], v148 offset:5120
	ds_read_b128 v[206:209], v148 offset:6144
	ds_read_b128 v[228:231], v148 offset:7168
	global_load_lds_dwordx4 v[186:187], off
	v_lshl_add_u64 v[186:187], s[72:73], 0, v[138:139]
	s_add_i32 m0, s19, 0xe000
	s_nop 0
	global_load_lds_dwordx4 v[186:187], off
	s_waitcnt vmcnt(8)
	s_waitcnt lgkmcnt(0)
	s_barrier
	s_waitcnt lgkmcnt(0)
	v_mfma_f32_16x16x32_bf16 v[124:127], v[142:145], v[178:181], v[124:127]
	v_mfma_f32_16x16x32_bf16 v[120:123], v[154:157], v[178:181], v[120:123]
	v_mfma_f32_16x16x32_bf16 v[116:119], v[142:145], v[190:193], v[116:119]
	v_mfma_f32_16x16x32_bf16 v[112:115], v[154:157], v[190:193], v[112:115]
	v_mfma_f32_16x16x32_bf16 v[108:111], v[142:145], v[198:201], v[108:111]
	v_mfma_f32_16x16x32_bf16 v[104:107], v[154:157], v[198:201], v[104:107]
	v_mfma_f32_16x16x32_bf16 v[100:103], v[142:145], v[206:209], v[100:103]
	v_mfma_f32_16x16x32_bf16 v[96:99], v[154:157], v[206:209], v[96:99]
	v_mfma_f32_16x16x32_bf16 v[124:127], v[150:153], v[182:185], v[124:127]
	v_mfma_f32_16x16x32_bf16 v[120:123], v[158:161], v[182:185], v[120:123]
	v_mfma_f32_16x16x32_bf16 v[116:119], v[150:153], v[194:197], v[116:119]
	v_mfma_f32_16x16x32_bf16 v[112:115], v[158:161], v[194:197], v[112:115]
	v_mfma_f32_16x16x32_bf16 v[108:111], v[150:153], v[202:205], v[108:111]
	v_mfma_f32_16x16x32_bf16 v[104:107], v[158:161], v[202:205], v[104:107]
	v_mfma_f32_16x16x32_bf16 v[100:103], v[150:153], v[228:231], v[100:103]
	v_mfma_f32_16x16x32_bf16 v[96:99], v[158:161], v[228:231], v[96:99]
	v_mfma_f32_16x16x32_bf16 v[92:95], v[162:165], v[178:181], v[92:95]
	v_mfma_f32_16x16x32_bf16 v[88:91], v[170:173], v[178:181], v[88:91]
	v_mfma_f32_16x16x32_bf16 v[84:87], v[162:165], v[190:193], v[84:87]
	v_mfma_f32_16x16x32_bf16 v[80:83], v[170:173], v[190:193], v[80:83]
	v_mfma_f32_16x16x32_bf16 v[76:79], v[162:165], v[198:201], v[76:79]
	v_mfma_f32_16x16x32_bf16 v[72:75], v[170:173], v[198:201], v[72:75]
	v_mfma_f32_16x16x32_bf16 v[68:71], v[162:165], v[206:209], v[68:71]
	v_mfma_f32_16x16x32_bf16 v[64:67], v[170:173], v[206:209], v[64:67]
	v_mfma_f32_16x16x32_bf16 v[92:95], v[166:169], v[182:185], v[92:95]
	v_mfma_f32_16x16x32_bf16 v[88:91], v[174:177], v[182:185], v[88:91]
	v_mfma_f32_16x16x32_bf16 v[84:87], v[166:169], v[194:197], v[84:87]
	v_mfma_f32_16x16x32_bf16 v[80:83], v[174:177], v[194:197], v[80:83]
	v_mfma_f32_16x16x32_bf16 v[76:79], v[166:169], v[202:205], v[76:79]
	v_mfma_f32_16x16x32_bf16 v[72:75], v[174:177], v[202:205], v[72:75]
	v_mfma_f32_16x16x32_bf16 v[68:71], v[166:169], v[228:231], v[68:71]
	v_mfma_f32_16x16x32_bf16 v[64:67], v[174:177], v[228:231], v[64:67]
	s_barrier
	s_add_i32 s84, s84, s18
	v_lshl_add_u64 v[186:187], s[58:59], 0, v[128:129]
	s_mov_b32 m0, s84
	ds_read_b128 v[178:181], v148 offset:16384
	ds_read_b128 v[182:185], v148 offset:17408
	ds_read_b128 v[190:193], v148 offset:18432
	ds_read_b128 v[194:197], v148 offset:19456
	ds_read_b128 v[198:201], v148 offset:20480
	ds_read_b128 v[202:205], v148 offset:21504
	ds_read_b128 v[206:209], v148 offset:22528
	ds_read_b128 v[228:231], v148 offset:23552
	global_load_lds_dwordx4 v[186:187], off
	s_add_i32 m0, s84, 0x2000
	s_add_u32 s84, s58, 0x40000
	v_lshl_add_u64 v[188:189], s[58:59], 0, v[130:131]
	s_addc_u32 s85, s59, 0
	s_add_i32 s96, s96, s18
	global_load_lds_dwordx4 v[188:189], off
	v_lshl_add_u64 v[210:211], s[84:85], 0, v[128:129]
	s_mov_b32 m0, s96
	v_lshl_add_u64 v[232:233], s[64:65], 0, v[132:133]
	global_load_lds_dwordx4 v[210:211], off
	v_lshl_add_u64 v[210:211], s[84:85], 0, v[130:131]
	s_add_i32 m0, s96, 0x2000
	s_nop 0
	global_load_lds_dwordx4 v[210:211], off
	v_lshl_add_u64 v[210:211], s[64:65], 0, v[134:135]
	s_mov_b32 m0, s19
	s_nop 0
	global_load_lds_dwordx4 v[210:211], off
	s_mov_b32 m0, s20
	s_nop 0
	global_load_lds_dwordx4 v[232:233], off
	s_waitcnt vmcnt(8)
	s_waitcnt lgkmcnt(0)
	s_barrier
; #define PG8_STAGE(bufoff, gbase, voff) do { _Pragma("unroll") for (int _i = 0; _i < 2; ++_i) \
;         __builtin_amdgcn_global_load_lds((const unsigned*)((const char*)(gbase) + (voff)[_i]), (PG8_LAS unsigned*)(lds + (bufoff) + ldsw + _i * 8192), 16, 0, 0); } while (0)
; #define PG8_LDA(dst, b, h) do { _Pragma("unroll") for (int m = 0; m < 4; ++m) _Pragma("unroll") for (int k = 0; k < 2; ++k) dst[m][k] = *(const PG8_LAS bf16x8*)(lds + PG8_SA(b, h) + aoff + m * 2048 + k * 1024); } while (0)
; #define PG8_LDB(dst, b, h) do { _Pragma("unroll") for (int n = 0; n < 2; ++n) _Pragma("unroll") for (int k = 0; k < 2; ++k) dst[n][k] = *(const PG8_LAS bf16x8*)(lds + PG8_SB(b, h) + boff + n * 2048 + k * 1024); } while (0)
; #define PG8_MMA(ai, bj, At, Bt) do { __builtin_amdgcn_s_setprio(1); _Pragma("unroll") for (int m = 0; m < 4; ++m) _Pragma("unroll") for (int n = 0; n < 2; ++n) _Pragma("unroll") for (int k = 0; k < 2; ++k) \
;         acc[ai][bj][m][n] = __builtin_amdgcn_mfma_f32_16x16x32_bf16(Bt[n][k], At[m][k], acc[ai][bj][m][n], 0, 0, 0); __builtin_amdgcn_s_setprio(0); } while (0)
; #define PG8_WAIT_V(n) asm volatile("s_waitcnt vmcnt(" #n ")" ::: "memory")
; #define PG8_WAIT_L(n) asm volatile("s_waitcnt lgkmcnt(" #n ")" ::: "memory")
; #define PG8_BAR __builtin_amdgcn_s_barrier()
; #define PG8_SCHED __builtin_amdgcn_sched_barrier(0)
; template <class Epi, class Sched, bool ALIGN_EPI = false, bool SP2 = false>
; __device__ __forceinline__ void gemm_phase(PG8_LAS unsigned char* lds, const Gemm g, const Sched& S, const Epi& E) {
;     ...
;             PG8_WAIT_V(8); PG8_WAIT_L(0); PG8_BAR; PG8_MMA(1, 0, At, B0); PG8_MMA(1, 1, At, B1); PG8_BAR; PG8_SCHED;
;             PG8_LDB(B0, 1, 0); PG8_LDB(B1, 1, 1); PG8_SCHED; PG8_LDA(At, 1, 0); PG8_STAGE(PG8_SA(0, 1), a2 + hstep, voffA);
;             PG8_WAIT_V(8); PG8_WAIT_L(0); PG8_BAR; PG8_MMA(0, 0, At, B0); PG8_MMA(0, 1, At, B1); PG8_BAR; PG8_SCHED;
	s_waitcnt lgkmcnt(0)
	v_mfma_f32_16x16x32_bf16 v[60:63], v[142:145], v[178:181], v[60:63]
	v_mfma_f32_16x16x32_bf16 v[56:59], v[154:157], v[178:181], v[56:59]
	v_mfma_f32_16x16x32_bf16 v[52:55], v[142:145], v[190:193], v[52:55]
	v_mfma_f32_16x16x32_bf16 v[48:51], v[154:157], v[190:193], v[48:51]
	v_mfma_f32_16x16x32_bf16 v[44:47], v[142:145], v[198:201], v[44:47]
	v_mfma_f32_16x16x32_bf16 v[40:43], v[154:157], v[198:201], v[40:43]
	v_mfma_f32_16x16x32_bf16 v[36:39], v[142:145], v[206:209], v[36:39]
	v_mfma_f32_16x16x32_bf16 v[32:35], v[154:157], v[206:209], v[32:35]
	v_mfma_f32_16x16x32_bf16 v[60:63], v[150:153], v[182:185], v[60:63]
	v_mfma_f32_16x16x32_bf16 v[56:59], v[158:161], v[182:185], v[56:59]
	v_mfma_f32_16x16x32_bf16 v[52:55], v[150:153], v[194:197], v[52:55]
	v_mfma_f32_16x16x32_bf16 v[48:51], v[158:161], v[194:197], v[48:51]
	v_mfma_f32_16x16x32_bf16 v[44:47], v[150:153], v[202:205], v[44:47]
	v_mfma_f32_16x16x32_bf16 v[40:43], v[158:161], v[202:205], v[40:43]
	v_mfma_f32_16x16x32_bf16 v[36:39], v[150:153], v[228:231], v[36:39]
	v_mfma_f32_16x16x32_bf16 v[32:35], v[158:161], v[228:231], v[32:35]
	v_mfma_f32_16x16x32_bf16 v[28:31], v[162:165], v[178:181], v[28:31]
	v_mfma_f32_16x16x32_bf16 v[24:27], v[170:173], v[178:181], v[24:27]
	v_mfma_f32_16x16x32_bf16 v[20:23], v[162:165], v[190:193], v[20:23]
	v_mfma_f32_16x16x32_bf16 v[16:19], v[170:173], v[190:193], v[16:19]
	v_mfma_f32_16x16x32_bf16 v[12:15], v[162:165], v[198:201], v[12:15]
	v_mfma_f32_16x16x32_bf16 v[8:11], v[170:173], v[198:201], v[8:11]
	v_mfma_f32_16x16x32_bf16 v[4:7], v[162:165], v[206:209], v[4:7]
	v_mfma_f32_16x16x32_bf16 v[0:3], v[170:173], v[206:209], v[0:3]
	v_mfma_f32_16x16x32_bf16 v[28:31], v[166:169], v[182:185], v[28:31]
	v_mfma_f32_16x16x32_bf16 v[24:27], v[174:177], v[182:185], v[24:27]
	v_mfma_f32_16x16x32_bf16 v[20:23], v[166:169], v[194:197], v[20:23]
	v_mfma_f32_16x16x32_bf16 v[16:19], v[174:177], v[194:197], v[16:19]
	v_mfma_f32_16x16x32_bf16 v[12:15], v[166:169], v[202:205], v[12:15]
	v_mfma_f32_16x16x32_bf16 v[8:11], v[174:177], v[202:205], v[8:11]
	v_mfma_f32_16x16x32_bf16 v[4:7], v[166:169], v[228:231], v[4:7]
	v_mfma_f32_16x16x32_bf16 v[0:3], v[174:177], v[228:231], v[0:3]
	s_barrier
	s_add_i32 s84, 0, 0x18000
	v_add_u32_e32 v140, s84, v146
	s_add_i32 s85, 0, 0x1c000
	ds_read_b128 v[142:145], v140
	ds_read_b128 v[150:153], v140 offset:1024
	ds_read_b128 v[154:157], v140 offset:2048
	ds_read_b128 v[158:161], v140 offset:3072
	v_add_u32_e32 v140, s85, v146
	ds_read_b128 v[162:165], v140
	ds_read_b128 v[166:169], v140 offset:1024
	ds_read_b128 v[170:173], v140 offset:2048
	ds_read_b128 v[174:177], v140 offset:3072
	s_add_u32 s64, s64, 0x40000
	s_addc_u32 s65, s65, 0
	s_mov_b32 m0, s21
	v_lshl_add_u64 v[234:235], s[64:65], 0, v[134:135]
	ds_read_b128 v[178:181], v148 offset:32768
	ds_read_b128 v[182:185], v148 offset:33792
	ds_read_b128 v[190:193], v148 offset:34816
	ds_read_b128 v[194:197], v148 offset:35840
	ds_read_b128 v[198:201], v148 offset:36864
	ds_read_b128 v[202:205], v148 offset:37888
	ds_read_b128 v[206:209], v148 offset:38912
	ds_read_b128 v[228:231], v148 offset:39936
	global_load_lds_dwordx4 v[234:235], off
	v_lshl_add_u64 v[234:235], s[64:65], 0, v[132:133]
	s_mov_b32 m0, s22
	s_nop 0
	global_load_lds_dwordx4 v[234:235], off
	s_waitcnt vmcnt(8)
	s_waitcnt lgkmcnt(0)
	s_barrier
	s_waitcnt lgkmcnt(0)
	v_mfma_f32_16x16x32_bf16 v[124:127], v[142:145], v[178:181], v[124:127]
	v_mfma_f32_16x16x32_bf16 v[120:123], v[154:157], v[178:181], v[120:123]
	v_mfma_f32_16x16x32_bf16 v[116:119], v[142:145], v[190:193], v[116:119]
	v_mfma_f32_16x16x32_bf16 v[112:115], v[154:157], v[190:193], v[112:115]
	v_mfma_f32_16x16x32_bf16 v[108:111], v[142:145], v[198:201], v[108:111]
	v_mfma_f32_16x16x32_bf16 v[104:107], v[154:157], v[198:201], v[104:107]
	v_mfma_f32_16x16x32_bf16 v[100:103], v[142:145], v[206:209], v[100:103]
	v_mfma_f32_16x16x32_bf16 v[96:99], v[154:157], v[206:209], v[96:99]
	v_mfma_f32_16x16x32_bf16 v[124:127], v[150:153], v[182:185], v[124:127]
	v_mfma_f32_16x16x32_bf16 v[120:123], v[158:161], v[182:185], v[120:123]
	v_mfma_f32_16x16x32_bf16 v[116:119], v[150:153], v[194:197], v[116:119]
	v_mfma_f32_16x16x32_bf16 v[112:115], v[158:161], v[194:197], v[112:115]
	v_mfma_f32_16x16x32_bf16 v[108:111], v[150:153], v[202:205], v[108:111]
	v_mfma_f32_16x16x32_bf16 v[104:107], v[158:161], v[202:205], v[104:107]
	v_mfma_f32_16x16x32_bf16 v[100:103], v[150:153], v[228:231], v[100:103]
	v_mfma_f32_16x16x32_bf16 v[96:99], v[158:161], v[228:231], v[96:99]
	v_mfma_f32_16x16x32_bf16 v[92:95], v[162:165], v[178:181], v[92:95]
	v_mfma_f32_16x16x32_bf16 v[88:91], v[170:173], v[178:181], v[88:91]
	v_mfma_f32_16x16x32_bf16 v[84:87], v[162:165], v[190:193], v[84:87]
	v_mfma_f32_16x16x32_bf16 v[80:83], v[170:173], v[190:193], v[80:83]
	v_mfma_f32_16x16x32_bf16 v[76:79], v[162:165], v[198:201], v[76:79]
	v_mfma_f32_16x16x32_bf16 v[72:75], v[170:173], v[198:201], v[72:75]
	v_mfma_f32_16x16x32_bf16 v[68:71], v[162:165], v[206:209], v[68:71]
	v_mfma_f32_16x16x32_bf16 v[64:67], v[170:173], v[206:209], v[64:67]
	v_mfma_f32_16x16x32_bf16 v[92:95], v[166:169], v[182:185], v[92:95]
	v_mfma_f32_16x16x32_bf16 v[88:91], v[174:177], v[182:185], v[88:91]
	v_mfma_f32_16x16x32_bf16 v[84:87], v[166:169], v[194:197], v[84:87]
	v_mfma_f32_16x16x32_bf16 v[80:83], v[174:177], v[194:197], v[80:83]
	v_mfma_f32_16x16x32_bf16 v[76:79], v[166:169], v[202:205], v[76:79]
	v_mfma_f32_16x16x32_bf16 v[72:75], v[174:177], v[202:205], v[72:75]
	v_mfma_f32_16x16x32_bf16 v[68:71], v[166:169], v[228:231], v[68:71]
	v_mfma_f32_16x16x32_bf16 v[64:67], v[174:177], v[228:231], v[64:67]
	s_barrier
; #define PG8_STAGE(bufoff, gbase, voff) do { _Pragma("unroll") for (int _i = 0; _i < 2; ++_i) \
;         __builtin_amdgcn_global_load_lds((const unsigned*)((const char*)(gbase) + (voff)[_i]), (PG8_LAS unsigned*)(lds + (bufoff) + ldsw + _i * 8192), 16, 0, 0); } while (0)
; #define PG8_LDA(dst, b, h) do { _Pragma("unroll") for (int m = 0; m < 4; ++m) _Pragma("unroll") for (int k = 0; k < 2; ++k) dst[m][k] = *(const PG8_LAS bf16x8*)(lds + PG8_SA(b, h) + aoff + m * 2048 + k * 1024); } while (0)
; #define PG8_MMA(ai, bj, At, Bt) do { __builtin_amdgcn_s_setprio(1); _Pragma("unroll") for (int m = 0; m < 4; ++m) _Pragma("unroll") for (int n = 0; n < 2; ++n) _Pragma("unroll") for (int k = 0; k < 2; ++k) \
;         acc[ai][bj][m][n] = __builtin_amdgcn_mfma_f32_16x16x32_bf16(Bt[n][k], At[m][k], acc[ai][bj][m][n], 0, 0, 0); __builtin_amdgcn_s_setprio(0); } while (0)
; #define PG8_WAIT_V(n) asm volatile("s_waitcnt vmcnt(" #n ")" ::: "memory")
; #define PG8_WAIT_L(n) asm volatile("s_waitcnt lgkmcnt(" #n ")" ::: "memory")
; #define PG8_BAR __builtin_amdgcn_s_barrier()
; #define PG8_SCHED __builtin_amdgcn_sched_barrier(0)
; template <class Epi, class Sched, bool ALIGN_EPI = false, bool SP2 = false>
; __device__ __forceinline__ void gemm_phase(PG8_LAS unsigned char* lds, const Gemm g, const Sched& S, const Epi& E) {
;     ...
;             PG8_LDA(At, 1, 1); PG8_STAGE(PG8_SB(1, 0), b3, voffB); PG8_STAGE(PG8_SB(1, 1), b3 + hstep, voffB); PG8_STAGE(PG8_SA(1, 0), a3, voffA);
;             PG8_WAIT_V(8); PG8_WAIT_L(0); PG8_BAR; PG8_MMA(1, 0, At, B0); PG8_MMA(1, 1, At, B1); PG8_BAR; PG8_SCHED;
	s_add_i32 s64, s84, s18
	v_lshl_add_u64 v[186:187], v[186:187], 0, s[90:91]
	s_mov_b32 m0, s64
	ds_read_b128 v[178:181], v148 offset:49152
	ds_read_b128 v[182:185], v148 offset:50176
	ds_read_b128 v[190:193], v148 offset:51200
	ds_read_b128 v[194:197], v148 offset:52224
	ds_read_b128 v[198:201], v148 offset:53248
	ds_read_b128 v[202:205], v148 offset:54272
	ds_read_b128 v[206:209], v148 offset:55296
	ds_read_b128 v[228:231], v148 offset:56320
	global_load_lds_dwordx4 v[186:187], off
	s_add_i32 m0, s64, 0x2000
	s_add_u32 s58, s58, 0x40080
	v_lshl_add_u64 v[186:187], v[188:189], 0, s[90:91]
	s_addc_u32 s59, s59, 0
	s_add_i32 s64, s85, s18
	global_load_lds_dwordx4 v[186:187], off
	v_lshl_add_u64 v[186:187], s[58:59], 0, v[128:129]
	s_mov_b32 m0, s64
	s_nop 0
	global_load_lds_dwordx4 v[186:187], off
	v_lshl_add_u64 v[186:187], s[58:59], 0, v[130:131]
	s_add_i32 m0, s64, 0x2000
	s_nop 0
	global_load_lds_dwordx4 v[186:187], off
	v_lshl_add_u64 v[186:187], v[210:211], 0, s[90:91]
	s_mov_b32 m0, s28
	s_nop 0
	global_load_lds_dwordx4 v[186:187], off
	v_lshl_add_u64 v[186:187], v[232:233], 0, s[90:91]
	s_mov_b32 m0, s29
	s_nop 0
	global_load_lds_dwordx4 v[186:187], off
	s_waitcnt vmcnt(8)
	s_waitcnt lgkmcnt(0)
	s_barrier
	s_waitcnt lgkmcnt(0)
	v_mfma_f32_16x16x32_bf16 v[60:63], v[142:145], v[178:181], v[60:63]
	v_mfma_f32_16x16x32_bf16 v[56:59], v[154:157], v[178:181], v[56:59]
	v_mfma_f32_16x16x32_bf16 v[52:55], v[142:145], v[190:193], v[52:55]
	v_mfma_f32_16x16x32_bf16 v[48:51], v[154:157], v[190:193], v[48:51]
	v_mfma_f32_16x16x32_bf16 v[44:47], v[142:145], v[198:201], v[44:47]
	v_mfma_f32_16x16x32_bf16 v[40:43], v[154:157], v[198:201], v[40:43]
	v_mfma_f32_16x16x32_bf16 v[36:39], v[142:145], v[206:209], v[36:39]
	v_mfma_f32_16x16x32_bf16 v[32:35], v[154:157], v[206:209], v[32:35]
	v_mfma_f32_16x16x32_bf16 v[60:63], v[150:153], v[182:185], v[60:63]
	v_mfma_f32_16x16x32_bf16 v[56:59], v[158:161], v[182:185], v[56:59]
	v_mfma_f32_16x16x32_bf16 v[52:55], v[150:153], v[194:197], v[52:55]
	v_mfma_f32_16x16x32_bf16 v[48:51], v[158:161], v[194:197], v[48:51]
	v_mfma_f32_16x16x32_bf16 v[44:47], v[150:153], v[202:205], v[44:47]
	v_mfma_f32_16x16x32_bf16 v[40:43], v[158:161], v[202:205], v[40:43]
	v_mfma_f32_16x16x32_bf16 v[36:39], v[150:153], v[228:231], v[36:39]
	v_mfma_f32_16x16x32_bf16 v[32:35], v[158:161], v[228:231], v[32:35]
	v_mfma_f32_16x16x32_bf16 v[28:31], v[162:165], v[178:181], v[28:31]
	v_mfma_f32_16x16x32_bf16 v[24:27], v[170:173], v[178:181], v[24:27]
	v_mfma_f32_16x16x32_bf16 v[20:23], v[162:165], v[190:193], v[20:23]
	v_mfma_f32_16x16x32_bf16 v[16:19], v[170:173], v[190:193], v[16:19]
	v_mfma_f32_16x16x32_bf16 v[12:15], v[162:165], v[198:201], v[12:15]
	v_mfma_f32_16x16x32_bf16 v[8:11], v[170:173], v[198:201], v[8:11]
	v_mfma_f32_16x16x32_bf16 v[4:7], v[162:165], v[206:209], v[4:7]
	v_mfma_f32_16x16x32_bf16 v[0:3], v[170:173], v[206:209], v[0:3]
	v_mfma_f32_16x16x32_bf16 v[28:31], v[166:169], v[182:185], v[28:31]
	v_mfma_f32_16x16x32_bf16 v[24:27], v[174:177], v[182:185], v[24:27]
	v_mfma_f32_16x16x32_bf16 v[20:23], v[166:169], v[194:197], v[20:23]
	v_mfma_f32_16x16x32_bf16 v[16:19], v[174:177], v[194:197], v[16:19]
	v_mfma_f32_16x16x32_bf16 v[12:15], v[166:169], v[202:205], v[12:15]
	v_mfma_f32_16x16x32_bf16 v[8:11], v[174:177], v[202:205], v[8:11]
	v_mfma_f32_16x16x32_bf16 v[4:7], v[166:169], v[228:231], v[4:7]
	v_mfma_f32_16x16x32_bf16 v[0:3], v[174:177], v[228:231], v[0:3]
	s_barrier
	s_add_i32 s94, s94, 2
	s_add_u32 s72, s72, 0x100
	s_addc_u32 s73, s73, 0
	s_add_u32 s92, s92, 0x100
	s_addc_u32 s93, s93, 0
	s_cmp_gt_u32 s94, 13
	s_cbranch_scc0 .LBB0_164
	s_and_b64 vcc, exec, s[48:49]
	s_cbranch_vccz .LBB0_167
	s_barrier

; #define PG8_STAGE(bufoff, gbase, voff) do { _Pragma("unroll") for (int _i = 0; _i < 2; ++_i) \
;         __builtin_amdgcn_global_load_lds((const unsigned*)((const char*)(gbase) + (voff)[_i]), (PG8_LAS unsigned*)(lds + (bufoff) + ldsw + _i * 8192), 16, 0, 0); } while (0)
; #define PG8_LDA(dst, b, h) do { _Pragma("unroll") for (int m = 0; m < 4; ++m) _Pragma("unroll") for (int k = 0; k < 2; ++k) dst[m][k] = *(const PG8_LAS bf16x8*)(lds + PG8_SA(b, h) + aoff + m * 2048 + k * 1024); } while (0)
; #define PG8_LDB(dst, b, h) do { _Pragma("unroll") for (int n = 0; n < 2; ++n) _Pragma("unroll") for (int k = 0; k < 2; ++k) dst[n][k] = *(const PG8_LAS bf16x8*)(lds + PG8_SB(b, h) + boff + n * 2048 + k * 1024); } while (0)
; #define PG8_MMA(ai, bj, At, Bt) do { __builtin_amdgcn_s_setprio(1); _Pragma("unroll") for (int m = 0; m < 4; ++m) _Pragma("unroll") for (int n = 0; n < 2; ++n) _Pragma("unroll") for (int k = 0; k < 2; ++k) \
;         acc[ai][bj][m][n] = __builtin_amdgcn_mfma_f32_16x16x32_bf16(Bt[n][k], At[m][k], acc[ai][bj][m][n], 0, 0, 0); __builtin_amdgcn_s_setprio(0); } while (0)
; #define PG8_WAIT_V(n) asm volatile("s_waitcnt vmcnt(" #n ")" ::: "memory")
; #define PG8_BAR __builtin_amdgcn_s_barrier()
; template <class Epi, class Sched, bool ALIGN_EPI = false, bool SP2 = false>
; __device__ __forceinline__ void gemm_phase(PG8_LAS unsigned char* lds, const Gemm g, const Sched& S, const Epi& E) {
;     ...
;         for (int t = 0; t < nt; t += 2) {
;             const bool last = (t == nt - 2);
;             const char* a1 = cA + (size_t)(t + 1) * kstep;
;             const char* a2 = last ? nA : cA + (size_t)(t + 2) * kstep; const char* b2 = last ? nB : cB + (size_t)(t + 2) * kstep;
;             const char* a3 = a2 + kstep; const char* b3 = b2 + kstep;
;             if (last && has_next) S.a_ready(nxt);
;             if constexpr (SP2) {
;             PG8_LDB(B0, 0, 0); PG8_LDB(B1, 0, 1); PG8_SCHED; PG8_LDA(At, 0, 0); PG8_STAGE(PG8_SA(1, 1), a1 + hstep, voffA);
;             PG8_WAIT_V(8); PG8_WAIT_L(0); PG8_BAR; PG8_MMA(0, 0, At, B0); PG8_MMA(0, 1, At, B1); PG8_BAR; PG8_SCHED;
;             PG8_LDA(At, 0, 1); PG8_STAGE(PG8_SB(0, 0), b2, voffB); PG8_STAGE(PG8_SB(0, 1), b2 + hstep, voffB); PG8_STAGE(PG8_SA(0, 0), a2, voffA);
;             PG8_WAIT_V(8); PG8_WAIT_L(0); PG8_BAR; PG8_MMA(1, 0, At, B0); PG8_MMA(1, 1, At, B1); PG8_BAR; PG8_SCHED;
.LBB0_564:
	s_add_u32 s44, vcc_lo, 0xfffc0080
	s_addc_u32 s45, vcc_hi, -1
	s_add_i32 s85, 0, 0x10000
	s_cmp_eq_u32 s84, 12
	s_cselect_b32 s93, s36, s45
	s_cselect_b32 s92, s37, s44
	s_cselect_b32 s59, s67, s94
	s_cselect_b32 s58, s73, s88
	s_add_i32 s8, 0, 0x14000
	v_add_u32_e32 v142, s85, v201
	v_add_u32_e32 v168, s8, v201
	ds_read_b128 v[130:133], v142
	ds_read_b128 v[134:137], v142 offset:1024
	ds_read_b128 v[138:141], v142 offset:2048
	ds_read_b128 v[142:145], v142 offset:3072
	ds_read_b128 v[156:159], v168
	ds_read_b128 v[160:163], v168 offset:1024
	ds_read_b128 v[164:167], v168 offset:2048
	ds_read_b128 v[168:171], v168 offset:3072
	v_lshl_add_u64 v[208:209], vcc, 0, v[152:153]
	s_add_i32 m0, s15, 0xc000
	ds_read_b128 v[172:175], v203
	ds_read_b128 v[176:179], v203 offset:1024
	ds_read_b128 v[180:183], v203 offset:2048
	ds_read_b128 v[184:187], v203 offset:3072
	ds_read_b128 v[188:191], v203 offset:4096
	ds_read_b128 v[192:195], v203 offset:5120
	ds_read_b128 v[196:199], v203 offset:6144
	ds_read_b128 v[204:207], v203 offset:7168
	global_load_lds_dwordx4 v[208:209], off
	v_lshl_add_u64 v[208:209], vcc, 0, v[154:155]
	s_add_i32 m0, s15, 0xe000
	s_nop 0
	global_load_lds_dwordx4 v[208:209], off
	s_waitcnt vmcnt(8)
	s_waitcnt lgkmcnt(0)
	s_barrier
	s_waitcnt lgkmcnt(0)
	v_mfma_f32_16x16x32_bf16 v[124:127], v[130:133], v[172:175], v[124:127]
	v_mfma_f32_16x16x32_bf16 v[120:123], v[138:141], v[172:175], v[120:123]
	v_mfma_f32_16x16x32_bf16 v[108:111], v[130:133], v[180:183], v[108:111]
	v_mfma_f32_16x16x32_bf16 v[104:107], v[138:141], v[180:183], v[104:107]
	v_mfma_f32_16x16x32_bf16 v[92:95], v[130:133], v[188:191], v[92:95]
	v_mfma_f32_16x16x32_bf16 v[88:91], v[138:141], v[188:191], v[88:91]
	v_mfma_f32_16x16x32_bf16 v[76:79], v[130:133], v[196:199], v[76:79]
	v_mfma_f32_16x16x32_bf16 v[72:75], v[138:141], v[196:199], v[72:75]
	v_mfma_f32_16x16x32_bf16 v[124:127], v[134:137], v[176:179], v[124:127]
	v_mfma_f32_16x16x32_bf16 v[120:123], v[142:145], v[176:179], v[120:123]
	v_mfma_f32_16x16x32_bf16 v[108:111], v[134:137], v[184:187], v[108:111]
	v_mfma_f32_16x16x32_bf16 v[104:107], v[142:145], v[184:187], v[104:107]
	v_mfma_f32_16x16x32_bf16 v[92:95], v[134:137], v[192:195], v[92:95]
	v_mfma_f32_16x16x32_bf16 v[88:91], v[142:145], v[192:195], v[88:91]
	v_mfma_f32_16x16x32_bf16 v[76:79], v[134:137], v[204:207], v[76:79]
	v_mfma_f32_16x16x32_bf16 v[72:75], v[142:145], v[204:207], v[72:75]
	v_mfma_f32_16x16x32_bf16 v[116:119], v[156:159], v[172:175], v[116:119]
	v_mfma_f32_16x16x32_bf16 v[112:115], v[164:167], v[172:175], v[112:115]
	v_mfma_f32_16x16x32_bf16 v[100:103], v[156:159], v[180:183], v[100:103]
	v_mfma_f32_16x16x32_bf16 v[96:99], v[164:167], v[180:183], v[96:99]
	v_mfma_f32_16x16x32_bf16 v[84:87], v[156:159], v[188:191], v[84:87]
	v_mfma_f32_16x16x32_bf16 v[80:83], v[164:167], v[188:191], v[80:83]
	v_mfma_f32_16x16x32_bf16 v[68:71], v[156:159], v[196:199], v[68:71]
	v_mfma_f32_16x16x32_bf16 v[64:67], v[164:167], v[196:199], v[64:67]
	v_mfma_f32_16x16x32_bf16 v[116:119], v[160:163], v[176:179], v[116:119]
	v_mfma_f32_16x16x32_bf16 v[112:115], v[168:171], v[176:179], v[112:115]
	v_mfma_f32_16x16x32_bf16 v[100:103], v[160:163], v[184:187], v[100:103]
	v_mfma_f32_16x16x32_bf16 v[96:99], v[168:171], v[184:187], v[96:99]
	v_mfma_f32_16x16x32_bf16 v[84:87], v[160:163], v[192:195], v[84:87]
	v_mfma_f32_16x16x32_bf16 v[80:83], v[168:171], v[192:195], v[80:83]
	v_mfma_f32_16x16x32_bf16 v[68:71], v[160:163], v[204:207], v[68:71]
	v_mfma_f32_16x16x32_bf16 v[64:67], v[168:171], v[204:207], v[64:67]
	s_barrier
	s_add_i32 s44, s85, s14
	v_lshl_add_u64 v[208:209], s[58:59], 0, v[128:129]
	s_mov_b32 m0, s44
	ds_read_b128 v[172:175], v203 offset:16384
	ds_read_b128 v[176:179], v203 offset:17408
	ds_read_b128 v[180:183], v203 offset:18432
	ds_read_b128 v[184:187], v203 offset:19456
	ds_read_b128 v[188:191], v203 offset:20480
	ds_read_b128 v[192:195], v203 offset:21504
	ds_read_b128 v[196:199], v203 offset:22528
	ds_read_b128 v[204:207], v203 offset:23552
	global_load_lds_dwordx4 v[208:209], off
	s_add_i32 m0, s44, 0x2000
	s_add_u32 s44, s58, 0x40000
	v_lshl_add_u64 v[210:211], s[58:59], 0, v[146:147]
	s_addc_u32 s45, s59, 0
	s_add_i32 s8, s8, s14
	global_load_lds_dwordx4 v[210:211], off
	v_lshl_add_u64 v[214:215], s[44:45], 0, v[128:129]
	s_mov_b32 m0, s8
	v_lshl_add_u64 v[222:223], s[92:93], 0, v[148:149]
	global_load_lds_dwordx4 v[214:215], off
	v_lshl_add_u64 v[214:215], s[44:45], 0, v[146:147]
	s_add_i32 m0, s8, 0x2000
	s_nop 0
	global_load_lds_dwordx4 v[214:215], off
	v_lshl_add_u64 v[214:215], s[92:93], 0, v[150:151]
	s_mov_b32 m0, s15
	s_nop 0
	global_load_lds_dwordx4 v[214:215], off
	s_mov_b32 m0, s17
	s_nop 0
	global_load_lds_dwordx4 v[222:223], off
	s_waitcnt vmcnt(8)
	s_waitcnt lgkmcnt(0)
	s_barrier
; #define PG8_STAGE(bufoff, gbase, voff) do { _Pragma("unroll") for (int _i = 0; _i < 2; ++_i) \
;         __builtin_amdgcn_global_load_lds((const unsigned*)((const char*)(gbase) + (voff)[_i]), (PG8_LAS unsigned*)(lds + (bufoff) + ldsw + _i * 8192), 16, 0, 0); } while (0)
; #define PG8_LDA(dst, b, h) do { _Pragma("unroll") for (int m = 0; m < 4; ++m) _Pragma("unroll") for (int k = 0; k < 2; ++k) dst[m][k] = *(const PG8_LAS bf16x8*)(lds + PG8_SA(b, h) + aoff + m * 2048 + k * 1024); } while (0)
; #define PG8_LDB(dst, b, h) do { _Pragma("unroll") for (int n = 0; n < 2; ++n) _Pragma("unroll") for (int k = 0; k < 2; ++k) dst[n][k] = *(const PG8_LAS bf16x8*)(lds + PG8_SB(b, h) + boff + n * 2048 + k * 1024); } while (0)
; #define PG8_MMA(ai, bj, At, Bt) do { __builtin_amdgcn_s_setprio(1); _Pragma("unroll") for (int m = 0; m < 4; ++m) _Pragma("unroll") for (int n = 0; n < 2; ++n) _Pragma("unroll") for (int k = 0; k < 2; ++k) \
;         acc[ai][bj][m][n] = __builtin_amdgcn_mfma_f32_16x16x32_bf16(Bt[n][k], At[m][k], acc[ai][bj][m][n], 0, 0, 0); __builtin_amdgcn_s_setprio(0); } while (0)
; #define PG8_WAIT_V(n) asm volatile("s_waitcnt vmcnt(" #n ")" ::: "memory")
; #define PG8_WAIT_L(n) asm volatile("s_waitcnt lgkmcnt(" #n ")" ::: "memory")
; #define PG8_BAR __builtin_amdgcn_s_barrier()
; #define PG8_SCHED __builtin_amdgcn_sched_barrier(0)
; template <class Epi, class Sched, bool ALIGN_EPI = false, bool SP2 = false>
; __device__ __forceinline__ void gemm_phase(PG8_LAS unsigned char* lds, const Gemm g, const Sched& S, const Epi& E) {
;     ...
;             PG8_WAIT_V(8); PG8_WAIT_L(0); PG8_BAR; PG8_MMA(1, 0, At, B0); PG8_MMA(1, 1, At, B1); PG8_BAR; PG8_SCHED;
;             PG8_LDB(B0, 1, 0); PG8_LDB(B1, 1, 1); PG8_SCHED; PG8_LDA(At, 1, 0); PG8_STAGE(PG8_SA(0, 1), a2 + hstep, voffA);
;             PG8_WAIT_V(8); PG8_WAIT_L(0); PG8_BAR; PG8_MMA(0, 0, At, B0); PG8_MMA(0, 1, At, B1); PG8_BAR; PG8_SCHED;
	s_waitcnt lgkmcnt(0)
	v_mfma_f32_16x16x32_bf16 v[60:63], v[130:133], v[172:175], v[60:63]
	v_mfma_f32_16x16x32_bf16 v[56:59], v[138:141], v[172:175], v[56:59]
	v_mfma_f32_16x16x32_bf16 v[44:47], v[130:133], v[180:183], v[44:47]
	v_mfma_f32_16x16x32_bf16 v[40:43], v[138:141], v[180:183], v[40:43]
	v_mfma_f32_16x16x32_bf16 v[28:31], v[130:133], v[188:191], v[28:31]
	v_mfma_f32_16x16x32_bf16 v[24:27], v[138:141], v[188:191], v[24:27]
	v_mfma_f32_16x16x32_bf16 v[12:15], v[130:133], v[196:199], v[12:15]
	v_mfma_f32_16x16x32_bf16 v[8:11], v[138:141], v[196:199], v[8:11]
	v_mfma_f32_16x16x32_bf16 v[60:63], v[134:137], v[176:179], v[60:63]
	v_mfma_f32_16x16x32_bf16 v[56:59], v[142:145], v[176:179], v[56:59]
	v_mfma_f32_16x16x32_bf16 v[44:47], v[134:137], v[184:187], v[44:47]
	v_mfma_f32_16x16x32_bf16 v[40:43], v[142:145], v[184:187], v[40:43]
	v_mfma_f32_16x16x32_bf16 v[28:31], v[134:137], v[192:195], v[28:31]
	v_mfma_f32_16x16x32_bf16 v[24:27], v[142:145], v[192:195], v[24:27]
	v_mfma_f32_16x16x32_bf16 v[12:15], v[134:137], v[204:207], v[12:15]
	v_mfma_f32_16x16x32_bf16 v[8:11], v[142:145], v[204:207], v[8:11]
	v_mfma_f32_16x16x32_bf16 v[52:55], v[156:159], v[172:175], v[52:55]
	v_mfma_f32_16x16x32_bf16 v[48:51], v[164:167], v[172:175], v[48:51]
	v_mfma_f32_16x16x32_bf16 v[36:39], v[156:159], v[180:183], v[36:39]
	v_mfma_f32_16x16x32_bf16 v[32:35], v[164:167], v[180:183], v[32:35]
	v_mfma_f32_16x16x32_bf16 v[20:23], v[156:159], v[188:191], v[20:23]
	v_mfma_f32_16x16x32_bf16 v[16:19], v[164:167], v[188:191], v[16:19]
	v_mfma_f32_16x16x32_bf16 v[4:7], v[156:159], v[196:199], v[4:7]
	v_mfma_f32_16x16x32_bf16 v[0:3], v[164:167], v[196:199], v[0:3]
	v_mfma_f32_16x16x32_bf16 v[52:55], v[160:163], v[176:179], v[52:55]
	v_mfma_f32_16x16x32_bf16 v[48:51], v[168:171], v[176:179], v[48:51]
	v_mfma_f32_16x16x32_bf16 v[36:39], v[160:163], v[184:187], v[36:39]
	v_mfma_f32_16x16x32_bf16 v[32:35], v[168:171], v[184:187], v[32:35]
	v_mfma_f32_16x16x32_bf16 v[20:23], v[160:163], v[192:195], v[20:23]
	v_mfma_f32_16x16x32_bf16 v[16:19], v[168:171], v[192:195], v[16:19]
	v_mfma_f32_16x16x32_bf16 v[4:7], v[160:163], v[204:207], v[4:7]
	v_mfma_f32_16x16x32_bf16 v[0:3], v[168:171], v[204:207], v[0:3]
	s_barrier
	s_add_i32 s8, 0, 0x18000
	s_add_i32 s85, 0, 0x1c000
	v_add_u32_e32 v142, s8, v201
	v_add_u32_e32 v168, s85, v201
	ds_read_b128 v[130:133], v142
	ds_read_b128 v[134:137], v142 offset:1024
	ds_read_b128 v[138:141], v142 offset:2048
	ds_read_b128 v[142:145], v142 offset:3072
	ds_read_b128 v[156:159], v168
	ds_read_b128 v[160:163], v168 offset:1024
	ds_read_b128 v[164:167], v168 offset:2048
	ds_read_b128 v[168:171], v168 offset:3072
	s_add_u32 s44, s92, 0x40000
	s_addc_u32 s45, s93, 0
	s_mov_b32 m0, s18
	v_lshl_add_u64 v[228:229], s[44:45], 0, v[150:151]
	ds_read_b128 v[172:175], v203 offset:32768
	ds_read_b128 v[176:179], v203 offset:33792
	ds_read_b128 v[180:183], v203 offset:34816
	ds_read_b128 v[184:187], v203 offset:35840
	ds_read_b128 v[188:191], v203 offset:36864
	ds_read_b128 v[192:195], v203 offset:37888
	ds_read_b128 v[196:199], v203 offset:38912
	ds_read_b128 v[204:207], v203 offset:39936
	global_load_lds_dwordx4 v[228:229], off
	v_lshl_add_u64 v[228:229], s[44:45], 0, v[148:149]
	s_mov_b32 m0, s19
	s_nop 0
	global_load_lds_dwordx4 v[228:229], off
	s_waitcnt vmcnt(8)
	s_waitcnt lgkmcnt(0)
	s_barrier
	s_waitcnt lgkmcnt(0)
	v_mfma_f32_16x16x32_bf16 v[124:127], v[130:133], v[172:175], v[124:127]
	v_mfma_f32_16x16x32_bf16 v[120:123], v[138:141], v[172:175], v[120:123]
	v_mfma_f32_16x16x32_bf16 v[108:111], v[130:133], v[180:183], v[108:111]
	v_mfma_f32_16x16x32_bf16 v[104:107], v[138:141], v[180:183], v[104:107]
	v_mfma_f32_16x16x32_bf16 v[92:95], v[130:133], v[188:191], v[92:95]
	v_mfma_f32_16x16x32_bf16 v[88:91], v[138:141], v[188:191], v[88:91]
	v_mfma_f32_16x16x32_bf16 v[76:79], v[130:133], v[196:199], v[76:79]
	v_mfma_f32_16x16x32_bf16 v[72:75], v[138:141], v[196:199], v[72:75]
	v_mfma_f32_16x16x32_bf16 v[124:127], v[134:137], v[176:179], v[124:127]
	v_mfma_f32_16x16x32_bf16 v[120:123], v[142:145], v[176:179], v[120:123]
	v_mfma_f32_16x16x32_bf16 v[108:111], v[134:137], v[184:187], v[108:111]
	v_mfma_f32_16x16x32_bf16 v[104:107], v[142:145], v[184:187], v[104:107]
	v_mfma_f32_16x16x32_bf16 v[92:95], v[134:137], v[192:195], v[92:95]
	v_mfma_f32_16x16x32_bf16 v[88:91], v[142:145], v[192:195], v[88:91]
	v_mfma_f32_16x16x32_bf16 v[76:79], v[134:137], v[204:207], v[76:79]
	v_mfma_f32_16x16x32_bf16 v[72:75], v[142:145], v[204:207], v[72:75]
	v_mfma_f32_16x16x32_bf16 v[116:119], v[156:159], v[172:175], v[116:119]
	v_mfma_f32_16x16x32_bf16 v[112:115], v[164:167], v[172:175], v[112:115]
	v_mfma_f32_16x16x32_bf16 v[100:103], v[156:159], v[180:183], v[100:103]
	v_mfma_f32_16x16x32_bf16 v[96:99], v[164:167], v[180:183], v[96:99]
	v_mfma_f32_16x16x32_bf16 v[84:87], v[156:159], v[188:191], v[84:87]
	v_mfma_f32_16x16x32_bf16 v[80:83], v[164:167], v[188:191], v[80:83]
	v_mfma_f32_16x16x32_bf16 v[68:71], v[156:159], v[196:199], v[68:71]
	v_mfma_f32_16x16x32_bf16 v[64:67], v[164:167], v[196:199], v[64:67]
	v_mfma_f32_16x16x32_bf16 v[116:119], v[160:163], v[176:179], v[116:119]
	v_mfma_f32_16x16x32_bf16 v[112:115], v[168:171], v[176:179], v[112:115]
	v_mfma_f32_16x16x32_bf16 v[100:103], v[160:163], v[184:187], v[100:103]
	v_mfma_f32_16x16x32_bf16 v[96:99], v[168:171], v[184:187], v[96:99]
	v_mfma_f32_16x16x32_bf16 v[84:87], v[160:163], v[192:195], v[84:87]
	v_mfma_f32_16x16x32_bf16 v[80:83], v[168:171], v[192:195], v[80:83]
	v_mfma_f32_16x16x32_bf16 v[68:71], v[160:163], v[204:207], v[68:71]
	v_mfma_f32_16x16x32_bf16 v[64:67], v[168:171], v[204:207], v[64:67]
	s_barrier
; #define PG8_STAGE(bufoff, gbase, voff) do { _Pragma("unroll") for (int _i = 0; _i < 2; ++_i) \
;         __builtin_amdgcn_global_load_lds((const unsigned*)((const char*)(gbase) + (voff)[_i]), (PG8_LAS unsigned*)(lds + (bufoff) + ldsw + _i * 8192), 16, 0, 0); } while (0)
; #define PG8_LDA(dst, b, h) do { _Pragma("unroll") for (int m = 0; m < 4; ++m) _Pragma("unroll") for (int k = 0; k < 2; ++k) dst[m][k] = *(const PG8_LAS bf16x8*)(lds + PG8_SA(b, h) + aoff + m * 2048 + k * 1024); } while (0)
; #define PG8_MMA(ai, bj, At, Bt) do { __builtin_amdgcn_s_setprio(1); _Pragma("unroll") for (int m = 0; m < 4; ++m) _Pragma("unroll") for (int n = 0; n < 2; ++n) _Pragma("unroll") for (int k = 0; k < 2; ++k) \
;         acc[ai][bj][m][n] = __builtin_amdgcn_mfma_f32_16x16x32_bf16(Bt[n][k], At[m][k], acc[ai][bj][m][n], 0, 0, 0); __builtin_amdgcn_s_setprio(0); } while (0)
; #define PG8_WAIT_V(n) asm volatile("s_waitcnt vmcnt(" #n ")" ::: "memory")
; #define PG8_WAIT_L(n) asm volatile("s_waitcnt lgkmcnt(" #n ")" ::: "memory")
; #define PG8_BAR __builtin_amdgcn_s_barrier()
; #define PG8_SCHED __builtin_amdgcn_sched_barrier(0)
; template <class Epi, class Sched, bool ALIGN_EPI = false, bool SP2 = false>
; __device__ __forceinline__ void gemm_phase(PG8_LAS unsigned char* lds, const Gemm g, const Sched& S, const Epi& E) {
;     ...
;             PG8_LDA(At, 1, 1); PG8_STAGE(PG8_SB(1, 0), b3, voffB); PG8_STAGE(PG8_SB(1, 1), b3 + hstep, voffB); PG8_STAGE(PG8_SA(1, 0), a3, voffA);
;             PG8_WAIT_V(8); PG8_WAIT_L(0); PG8_BAR; PG8_MMA(1, 0, At, B0); PG8_MMA(1, 1, At, B1); PG8_BAR; PG8_SCHED;
	s_add_i32 s8, s8, s14
	v_lshl_add_u64 v[208:209], v[208:209], 0, s[90:91]
	s_mov_b32 m0, s8
	ds_read_b128 v[172:175], v203 offset:49152
	ds_read_b128 v[176:179], v203 offset:50176
	ds_read_b128 v[180:183], v203 offset:51200
	ds_read_b128 v[184:187], v203 offset:52224
	ds_read_b128 v[188:191], v203 offset:53248
	ds_read_b128 v[192:195], v203 offset:54272
	ds_read_b128 v[196:199], v203 offset:55296
	ds_read_b128 v[204:207], v203 offset:56320
	global_load_lds_dwordx4 v[208:209], off
	s_add_i32 m0, s8, 0x2000
	s_add_u32 s44, s58, 0x40080
	v_lshl_add_u64 v[208:209], v[210:211], 0, s[90:91]
	s_addc_u32 s45, s59, 0
	s_add_i32 s8, s85, s14
	global_load_lds_dwordx4 v[208:209], off
	v_lshl_add_u64 v[208:209], s[44:45], 0, v[128:129]
	s_mov_b32 m0, s8
	s_nop 0
	global_load_lds_dwordx4 v[208:209], off
	v_lshl_add_u64 v[208:209], s[44:45], 0, v[146:147]
	s_add_i32 m0, s8, 0x2000
	s_nop 0
	global_load_lds_dwordx4 v[208:209], off
	v_lshl_add_u64 v[208:209], v[214:215], 0, s[90:91]
	s_mov_b32 m0, s30
	s_nop 0
	global_load_lds_dwordx4 v[208:209], off
	v_lshl_add_u64 v[208:209], v[222:223], 0, s[90:91]
	s_mov_b32 m0, s31
	s_nop 0
	global_load_lds_dwordx4 v[208:209], off
	s_waitcnt vmcnt(8)
	s_waitcnt lgkmcnt(0)
	s_barrier
	s_waitcnt lgkmcnt(0)
	v_mfma_f32_16x16x32_bf16 v[60:63], v[130:133], v[172:175], v[60:63]
	v_mfma_f32_16x16x32_bf16 v[56:59], v[138:141], v[172:175], v[56:59]
	v_mfma_f32_16x16x32_bf16 v[44:47], v[130:133], v[180:183], v[44:47]
	v_mfma_f32_16x16x32_bf16 v[40:43], v[138:141], v[180:183], v[40:43]
	v_mfma_f32_16x16x32_bf16 v[28:31], v[130:133], v[188:191], v[28:31]
	v_mfma_f32_16x16x32_bf16 v[24:27], v[138:141], v[188:191], v[24:27]
	v_mfma_f32_16x16x32_bf16 v[12:15], v[130:133], v[196:199], v[12:15]
	v_mfma_f32_16x16x32_bf16 v[8:11], v[138:141], v[196:199], v[8:11]
	v_mfma_f32_16x16x32_bf16 v[60:63], v[134:137], v[176:179], v[60:63]
	v_mfma_f32_16x16x32_bf16 v[56:59], v[142:145], v[176:179], v[56:59]
	v_mfma_f32_16x16x32_bf16 v[44:47], v[134:137], v[184:187], v[44:47]
	v_mfma_f32_16x16x32_bf16 v[40:43], v[142:145], v[184:187], v[40:43]
	v_mfma_f32_16x16x32_bf16 v[28:31], v[134:137], v[192:195], v[28:31]
	v_mfma_f32_16x16x32_bf16 v[24:27], v[142:145], v[192:195], v[24:27]
	v_mfma_f32_16x16x32_bf16 v[12:15], v[134:137], v[204:207], v[12:15]
	v_mfma_f32_16x16x32_bf16 v[8:11], v[142:145], v[204:207], v[8:11]
	v_mfma_f32_16x16x32_bf16 v[52:55], v[156:159], v[172:175], v[52:55]
	v_mfma_f32_16x16x32_bf16 v[48:51], v[164:167], v[172:175], v[48:51]
	v_mfma_f32_16x16x32_bf16 v[36:39], v[156:159], v[180:183], v[36:39]
	v_mfma_f32_16x16x32_bf16 v[32:35], v[164:167], v[180:183], v[32:35]
	v_mfma_f32_16x16x32_bf16 v[20:23], v[156:159], v[188:191], v[20:23]
	v_mfma_f32_16x16x32_bf16 v[16:19], v[164:167], v[188:191], v[16:19]
	v_mfma_f32_16x16x32_bf16 v[4:7], v[156:159], v[196:199], v[4:7]
	v_mfma_f32_16x16x32_bf16 v[0:3], v[164:167], v[196:199], v[0:3]
	v_mfma_f32_16x16x32_bf16 v[52:55], v[160:163], v[176:179], v[52:55]
	v_mfma_f32_16x16x32_bf16 v[48:51], v[168:171], v[176:179], v[48:51]
	v_mfma_f32_16x16x32_bf16 v[36:39], v[160:163], v[184:187], v[36:39]
	v_mfma_f32_16x16x32_bf16 v[32:35], v[168:171], v[184:187], v[32:35]
	v_mfma_f32_16x16x32_bf16 v[20:23], v[160:163], v[192:195], v[20:23]
	v_mfma_f32_16x16x32_bf16 v[16:19], v[168:171], v[192:195], v[16:19]
	v_mfma_f32_16x16x32_bf16 v[4:7], v[160:163], v[204:207], v[4:7]
	v_mfma_f32_16x16x32_bf16 v[0:3], v[168:171], v[204:207], v[0:3]
	s_barrier
	s_add_i32 s84, s84, 2
	s_add_u32 vcc_lo, vcc_lo, 0x100
	s_addc_u32 vcc_hi, vcc_hi, 0
	s_add_u32 s88, s88, 0x100
	s_addc_u32 s94, s94, 0
	s_cmp_gt_u32 s84, 13
	s_cbranch_scc0 .LBB0_564
	s_and_b64 vcc, exec, s[62:63]
	s_cbranch_vccz .LBB0_567
	s_barrier

; #define PG8_STAGE(bufoff, gbase, voff) do { _Pragma("unroll") for (int _i = 0; _i < 2; ++_i) \
;         __builtin_amdgcn_global_load_lds((const unsigned*)((const char*)(gbase) + (voff)[_i]), (PG8_LAS unsigned*)(lds + (bufoff) + ldsw + _i * 8192), 16, 0, 0); } while (0)
; #define PG8_LDA(dst, b, h) do { _Pragma("unroll") for (int m = 0; m < 4; ++m) _Pragma("unroll") for (int k = 0; k < 2; ++k) dst[m][k] = *(const PG8_LAS bf16x8*)(lds + PG8_SA(b, h) + aoff + m * 2048 + k * 1024); } while (0)
; #define PG8_LDB(dst, b, h) do { _Pragma("unroll") for (int n = 0; n < 2; ++n) _Pragma("unroll") for (int k = 0; k < 2; ++k) dst[n][k] = *(const PG8_LAS bf16x8*)(lds + PG8_SB(b, h) + boff + n * 2048 + k * 1024); } while (0)
; #define PG8_MMA(ai, bj, At, Bt) do { __builtin_amdgcn_s_setprio(1); _Pragma("unroll") for (int m = 0; m < 4; ++m) _Pragma("unroll") for (int n = 0; n < 2; ++n) _Pragma("unroll") for (int k = 0; k < 2; ++k) \
;         acc[ai][bj][m][n] = __builtin_amdgcn_mfma_f32_16x16x32_bf16(Bt[n][k], At[m][k], acc[ai][bj][m][n], 0, 0, 0); __builtin_amdgcn_s_setprio(0); } while (0)
; #define PG8_WAIT_V(n) asm volatile("s_waitcnt vmcnt(" #n ")" ::: "memory")
; #define PG8_BAR __builtin_amdgcn_s_barrier()
; template <class Epi, class Sched, bool ALIGN_EPI = false, bool SP2 = false>
; __device__ __forceinline__ void gemm_phase(PG8_LAS unsigned char* lds, const Gemm g, const Sched& S, const Epi& E) {
;     ...
;         for (int t = 0; t < nt; t += 2) {
;             const bool last = (t == nt - 2);
;             const char* a1 = cA + (size_t)(t + 1) * kstep;
;             const char* a2 = last ? nA : cA + (size_t)(t + 2) * kstep; const char* b2 = last ? nB : cB + (size_t)(t + 2) * kstep;
;             const char* a3 = a2 + kstep; const char* b3 = b2 + kstep;
;             if (last && has_next) S.a_ready(nxt);
;             if constexpr (SP2) {
;             PG8_LDB(B0, 0, 0); PG8_LDB(B1, 0, 1); PG8_SCHED; PG8_LDA(At, 0, 0); PG8_STAGE(PG8_SA(1, 1), a1 + hstep, voffA);
;             PG8_WAIT_V(8); PG8_WAIT_L(0); PG8_BAR; PG8_MMA(0, 0, At, B0); PG8_MMA(0, 1, At, B1); PG8_BAR; PG8_SCHED;
;             PG8_LDA(At, 0, 1); PG8_STAGE(PG8_SB(0, 0), b2, voffB); PG8_STAGE(PG8_SB(0, 1), b2 + hstep, voffB); PG8_STAGE(PG8_SA(0, 0), a2, voffA);
;             PG8_WAIT_V(8); PG8_WAIT_L(0); PG8_BAR; PG8_MMA(1, 0, At, B0); PG8_MMA(1, 1, At, B1); PG8_BAR; PG8_SCHED;
.LBB0_598:
	s_add_u32 s58, vcc_lo, 0xfffc0080
	s_addc_u32 s59, vcc_hi, -1
	s_add_i32 s84, 0, 0x10000
	s_cmp_eq_u32 s94, 12
	s_cselect_b32 s65, s35, s59
	s_cselect_b32 s64, s36, s58
	s_cselect_b32 s59, s37, s93
	s_cselect_b32 s58, s43, s88
	s_add_i32 s97, 0, 0x14000
	v_add_u32_e32 v76, s84, v228
	v_add_u32_e32 v168, s97, v228
	ds_read_b128 v[64:67], v76
	ds_read_b128 v[68:71], v76 offset:1024
	ds_read_b128 v[72:75], v76 offset:2048
	ds_read_b128 v[76:79], v76 offset:3072
	ds_read_b128 v[156:159], v168
	ds_read_b128 v[160:163], v168 offset:1024
	ds_read_b128 v[164:167], v168 offset:2048
	ds_read_b128 v[168:171], v168 offset:3072
	v_lshl_add_u64 v[204:205], vcc, 0, v[152:153]
	s_add_i32 m0, s18, 0xc000
	ds_read_b128 v[172:175], v230
	ds_read_b128 v[176:179], v230 offset:1024
	ds_read_b128 v[180:183], v230 offset:2048
	ds_read_b128 v[184:187], v230 offset:3072
	ds_read_b128 v[188:191], v230 offset:4096
	ds_read_b128 v[192:195], v230 offset:5120
	ds_read_b128 v[196:199], v230 offset:6144
	ds_read_b128 v[200:203], v230 offset:7168
	global_load_lds_dwordx4 v[204:205], off
	v_lshl_add_u64 v[204:205], vcc, 0, v[154:155]
	s_add_i32 m0, s18, 0xe000
	s_nop 0
	global_load_lds_dwordx4 v[204:205], off
	s_waitcnt vmcnt(8)
	s_waitcnt lgkmcnt(0)
	s_barrier
	s_waitcnt lgkmcnt(0)
	v_mfma_f32_16x16x32_bf16 v[142:145], v[64:67], v[172:175], v[142:145]
	v_mfma_f32_16x16x32_bf16 v[138:141], v[72:75], v[172:175], v[138:141]
	v_mfma_f32_16x16x32_bf16 v[134:137], v[64:67], v[180:183], v[134:137]
	v_mfma_f32_16x16x32_bf16 v[124:127], v[72:75], v[180:183], v[124:127]
	v_mfma_f32_16x16x32_bf16 v[108:111], v[64:67], v[188:191], v[108:111]
	v_mfma_f32_16x16x32_bf16 v[104:107], v[72:75], v[188:191], v[104:107]
	v_mfma_f32_16x16x32_bf16 v[100:103], v[64:67], v[196:199], v[100:103]
	v_mfma_f32_16x16x32_bf16 v[92:95], v[72:75], v[196:199], v[92:95]
	v_mfma_f32_16x16x32_bf16 v[142:145], v[68:71], v[176:179], v[142:145]
	v_mfma_f32_16x16x32_bf16 v[138:141], v[76:79], v[176:179], v[138:141]
	v_mfma_f32_16x16x32_bf16 v[134:137], v[68:71], v[184:187], v[134:137]
	v_mfma_f32_16x16x32_bf16 v[124:127], v[76:79], v[184:187], v[124:127]
	v_mfma_f32_16x16x32_bf16 v[108:111], v[68:71], v[192:195], v[108:111]
	v_mfma_f32_16x16x32_bf16 v[104:107], v[76:79], v[192:195], v[104:107]
	v_mfma_f32_16x16x32_bf16 v[100:103], v[68:71], v[200:203], v[100:103]
	v_mfma_f32_16x16x32_bf16 v[92:95], v[76:79], v[200:203], v[92:95]
	v_mfma_f32_16x16x32_bf16 v[130:133], v[156:159], v[172:175], v[130:133]
	v_mfma_f32_16x16x32_bf16 v[120:123], v[164:167], v[172:175], v[120:123]
	v_mfma_f32_16x16x32_bf16 v[116:119], v[156:159], v[180:183], v[116:119]
	v_mfma_f32_16x16x32_bf16 v[112:115], v[164:167], v[180:183], v[112:115]
	v_mfma_f32_16x16x32_bf16 v[96:99], v[156:159], v[188:191], v[96:99]
	v_mfma_f32_16x16x32_bf16 v[88:91], v[164:167], v[188:191], v[88:91]
	v_mfma_f32_16x16x32_bf16 v[84:87], v[156:159], v[196:199], v[84:87]
	v_mfma_f32_16x16x32_bf16 v[80:83], v[164:167], v[196:199], v[80:83]
	v_mfma_f32_16x16x32_bf16 v[130:133], v[160:163], v[176:179], v[130:133]
	v_mfma_f32_16x16x32_bf16 v[120:123], v[168:171], v[176:179], v[120:123]
	v_mfma_f32_16x16x32_bf16 v[116:119], v[160:163], v[184:187], v[116:119]
	v_mfma_f32_16x16x32_bf16 v[112:115], v[168:171], v[184:187], v[112:115]
	v_mfma_f32_16x16x32_bf16 v[96:99], v[160:163], v[192:195], v[96:99]
	v_mfma_f32_16x16x32_bf16 v[88:91], v[168:171], v[192:195], v[88:91]
	v_mfma_f32_16x16x32_bf16 v[84:87], v[160:163], v[200:203], v[84:87]
	v_mfma_f32_16x16x32_bf16 v[80:83], v[168:171], v[200:203], v[80:83]
	s_barrier
	s_add_i32 s84, s84, s17
	v_lshl_add_u64 v[204:205], s[58:59], 0, v[128:129]
	s_mov_b32 m0, s84
	ds_read_b128 v[172:175], v230 offset:16384
	ds_read_b128 v[176:179], v230 offset:17408
	ds_read_b128 v[180:183], v230 offset:18432
	ds_read_b128 v[184:187], v230 offset:19456
	ds_read_b128 v[188:191], v230 offset:20480
	ds_read_b128 v[192:195], v230 offset:21504
	ds_read_b128 v[196:199], v230 offset:22528
	ds_read_b128 v[200:203], v230 offset:23552
	global_load_lds_dwordx4 v[204:205], off
	s_add_i32 m0, s84, 0x2000
	s_add_u32 s84, s58, 0x40000
	v_lshl_add_u64 v[206:207], s[58:59], 0, v[146:147]
	s_addc_u32 s85, s59, 0
	s_add_i32 s97, s97, s17
	global_load_lds_dwordx4 v[206:207], off
	v_lshl_add_u64 v[208:209], s[84:85], 0, v[128:129]
	s_mov_b32 m0, s97
	v_lshl_add_u64 v[210:211], s[64:65], 0, v[148:149]
	global_load_lds_dwordx4 v[208:209], off
	v_lshl_add_u64 v[208:209], s[84:85], 0, v[146:147]
	s_add_i32 m0, s97, 0x2000
	s_nop 0
	global_load_lds_dwordx4 v[208:209], off
	v_lshl_add_u64 v[208:209], s[64:65], 0, v[150:151]
	s_mov_b32 m0, s18
	s_nop 0
	global_load_lds_dwordx4 v[208:209], off
	s_mov_b32 m0, s19
	s_nop 0
	global_load_lds_dwordx4 v[210:211], off
	s_waitcnt vmcnt(8)
	s_waitcnt lgkmcnt(0)
	s_barrier
; #define PG8_STAGE(bufoff, gbase, voff) do { _Pragma("unroll") for (int _i = 0; _i < 2; ++_i) \
;         __builtin_amdgcn_global_load_lds((const unsigned*)((const char*)(gbase) + (voff)[_i]), (PG8_LAS unsigned*)(lds + (bufoff) + ldsw + _i * 8192), 16, 0, 0); } while (0)
; #define PG8_LDA(dst, b, h) do { _Pragma("unroll") for (int m = 0; m < 4; ++m) _Pragma("unroll") for (int k = 0; k < 2; ++k) dst[m][k] = *(const PG8_LAS bf16x8*)(lds + PG8_SA(b, h) + aoff + m * 2048 + k * 1024); } while (0)
; #define PG8_LDB(dst, b, h) do { _Pragma("unroll") for (int n = 0; n < 2; ++n) _Pragma("unroll") for (int k = 0; k < 2; ++k) dst[n][k] = *(const PG8_LAS bf16x8*)(lds + PG8_SB(b, h) + boff + n * 2048 + k * 1024); } while (0)
; #define PG8_MMA(ai, bj, At, Bt) do { __builtin_amdgcn_s_setprio(1); _Pragma("unroll") for (int m = 0; m < 4; ++m) _Pragma("unroll") for (int n = 0; n < 2; ++n) _Pragma("unroll") for (int k = 0; k < 2; ++k) \
;         acc[ai][bj][m][n] = __builtin_amdgcn_mfma_f32_16x16x32_bf16(Bt[n][k], At[m][k], acc[ai][bj][m][n], 0, 0, 0); __builtin_amdgcn_s_setprio(0); } while (0)
; #define PG8_WAIT_V(n) asm volatile("s_waitcnt vmcnt(" #n ")" ::: "memory")
; #define PG8_WAIT_L(n) asm volatile("s_waitcnt lgkmcnt(" #n ")" ::: "memory")
; #define PG8_BAR __builtin_amdgcn_s_barrier()
; #define PG8_SCHED __builtin_amdgcn_sched_barrier(0)
; template <class Epi, class Sched, bool ALIGN_EPI = false, bool SP2 = false>
; __device__ __forceinline__ void gemm_phase(PG8_LAS unsigned char* lds, const Gemm g, const Sched& S, const Epi& E) {
;     ...
;             PG8_WAIT_V(8); PG8_WAIT_L(0); PG8_BAR; PG8_MMA(1, 0, At, B0); PG8_MMA(1, 1, At, B1); PG8_BAR; PG8_SCHED;
;             PG8_LDB(B0, 1, 0); PG8_LDB(B1, 1, 1); PG8_SCHED; PG8_LDA(At, 1, 0); PG8_STAGE(PG8_SA(0, 1), a2 + hstep, voffA);
;             PG8_WAIT_V(8); PG8_WAIT_L(0); PG8_BAR; PG8_MMA(0, 0, At, B0); PG8_MMA(0, 1, At, B1); PG8_BAR; PG8_SCHED;
	s_waitcnt lgkmcnt(0)
	v_mfma_f32_16x16x32_bf16 v[60:63], v[64:67], v[172:175], v[60:63]
	v_mfma_f32_16x16x32_bf16 v[56:59], v[72:75], v[172:175], v[56:59]
	v_mfma_f32_16x16x32_bf16 v[52:55], v[64:67], v[180:183], v[52:55]
	v_mfma_f32_16x16x32_bf16 v[44:47], v[72:75], v[180:183], v[44:47]
	v_mfma_f32_16x16x32_bf16 v[28:31], v[64:67], v[188:191], v[28:31]
	v_mfma_f32_16x16x32_bf16 v[24:27], v[72:75], v[188:191], v[24:27]
	v_mfma_f32_16x16x32_bf16 v[12:15], v[64:67], v[196:199], v[12:15]
	v_mfma_f32_16x16x32_bf16 v[8:11], v[72:75], v[196:199], v[8:11]
	v_mfma_f32_16x16x32_bf16 v[60:63], v[68:71], v[176:179], v[60:63]
	v_mfma_f32_16x16x32_bf16 v[56:59], v[76:79], v[176:179], v[56:59]
	v_mfma_f32_16x16x32_bf16 v[52:55], v[68:71], v[184:187], v[52:55]
	v_mfma_f32_16x16x32_bf16 v[44:47], v[76:79], v[184:187], v[44:47]
	v_mfma_f32_16x16x32_bf16 v[28:31], v[68:71], v[192:195], v[28:31]
	v_mfma_f32_16x16x32_bf16 v[24:27], v[76:79], v[192:195], v[24:27]
	v_mfma_f32_16x16x32_bf16 v[12:15], v[68:71], v[200:203], v[12:15]
	v_mfma_f32_16x16x32_bf16 v[8:11], v[76:79], v[200:203], v[8:11]
	v_mfma_f32_16x16x32_bf16 v[48:51], v[156:159], v[172:175], v[48:51]
	v_mfma_f32_16x16x32_bf16 v[40:43], v[164:167], v[172:175], v[40:43]
	v_mfma_f32_16x16x32_bf16 v[36:39], v[156:159], v[180:183], v[36:39]
	v_mfma_f32_16x16x32_bf16 v[32:35], v[164:167], v[180:183], v[32:35]
	v_mfma_f32_16x16x32_bf16 v[20:23], v[156:159], v[188:191], v[20:23]
	v_mfma_f32_16x16x32_bf16 v[16:19], v[164:167], v[188:191], v[16:19]
	v_mfma_f32_16x16x32_bf16 v[4:7], v[156:159], v[196:199], v[4:7]
	v_mfma_f32_16x16x32_bf16 v[0:3], v[164:167], v[196:199], v[0:3]
	v_mfma_f32_16x16x32_bf16 v[48:51], v[160:163], v[176:179], v[48:51]
	v_mfma_f32_16x16x32_bf16 v[40:43], v[168:171], v[176:179], v[40:43]
	v_mfma_f32_16x16x32_bf16 v[36:39], v[160:163], v[184:187], v[36:39]
	v_mfma_f32_16x16x32_bf16 v[32:35], v[168:171], v[184:187], v[32:35]
	v_mfma_f32_16x16x32_bf16 v[20:23], v[160:163], v[192:195], v[20:23]
	v_mfma_f32_16x16x32_bf16 v[16:19], v[168:171], v[192:195], v[16:19]
	v_mfma_f32_16x16x32_bf16 v[4:7], v[160:163], v[200:203], v[4:7]
	v_mfma_f32_16x16x32_bf16 v[0:3], v[168:171], v[200:203], v[0:3]
	s_barrier
	s_add_i32 s84, 0, 0x18000
	s_add_i32 s85, 0, 0x1c000
	v_add_u32_e32 v76, s84, v228
	v_add_u32_e32 v168, s85, v228
	ds_read_b128 v[64:67], v76
	ds_read_b128 v[68:71], v76 offset:1024
	ds_read_b128 v[72:75], v76 offset:2048
	ds_read_b128 v[76:79], v76 offset:3072
	ds_read_b128 v[156:159], v168
	ds_read_b128 v[160:163], v168 offset:1024
	ds_read_b128 v[164:167], v168 offset:2048
	ds_read_b128 v[168:171], v168 offset:3072
	s_add_u32 s64, s64, 0x40000
	s_addc_u32 s65, s65, 0
	s_mov_b32 m0, s20
	v_lshl_add_u64 v[214:215], s[64:65], 0, v[150:151]
	ds_read_b128 v[172:175], v230 offset:32768
	ds_read_b128 v[176:179], v230 offset:33792
	ds_read_b128 v[180:183], v230 offset:34816
	ds_read_b128 v[184:187], v230 offset:35840
	ds_read_b128 v[188:191], v230 offset:36864
	ds_read_b128 v[192:195], v230 offset:37888
	ds_read_b128 v[196:199], v230 offset:38912
	ds_read_b128 v[200:203], v230 offset:39936
	global_load_lds_dwordx4 v[214:215], off
	v_lshl_add_u64 v[214:215], s[64:65], 0, v[148:149]
	s_mov_b32 m0, s21
	s_nop 0
	global_load_lds_dwordx4 v[214:215], off
	s_waitcnt vmcnt(8)
	s_waitcnt lgkmcnt(0)
	s_barrier
	s_waitcnt lgkmcnt(0)
	v_mfma_f32_16x16x32_bf16 v[142:145], v[64:67], v[172:175], v[142:145]
	v_mfma_f32_16x16x32_bf16 v[138:141], v[72:75], v[172:175], v[138:141]
	v_mfma_f32_16x16x32_bf16 v[134:137], v[64:67], v[180:183], v[134:137]
	v_mfma_f32_16x16x32_bf16 v[124:127], v[72:75], v[180:183], v[124:127]
	v_mfma_f32_16x16x32_bf16 v[108:111], v[64:67], v[188:191], v[108:111]
	v_mfma_f32_16x16x32_bf16 v[104:107], v[72:75], v[188:191], v[104:107]
	v_mfma_f32_16x16x32_bf16 v[100:103], v[64:67], v[196:199], v[100:103]
	v_mfma_f32_16x16x32_bf16 v[92:95], v[72:75], v[196:199], v[92:95]
	v_mfma_f32_16x16x32_bf16 v[142:145], v[68:71], v[176:179], v[142:145]
	v_mfma_f32_16x16x32_bf16 v[138:141], v[76:79], v[176:179], v[138:141]
	v_mfma_f32_16x16x32_bf16 v[134:137], v[68:71], v[184:187], v[134:137]
	v_mfma_f32_16x16x32_bf16 v[124:127], v[76:79], v[184:187], v[124:127]
	v_mfma_f32_16x16x32_bf16 v[108:111], v[68:71], v[192:195], v[108:111]
	v_mfma_f32_16x16x32_bf16 v[104:107], v[76:79], v[192:195], v[104:107]
	v_mfma_f32_16x16x32_bf16 v[100:103], v[68:71], v[200:203], v[100:103]
	v_mfma_f32_16x16x32_bf16 v[92:95], v[76:79], v[200:203], v[92:95]
	v_mfma_f32_16x16x32_bf16 v[130:133], v[156:159], v[172:175], v[130:133]
	v_mfma_f32_16x16x32_bf16 v[120:123], v[164:167], v[172:175], v[120:123]
	v_mfma_f32_16x16x32_bf16 v[116:119], v[156:159], v[180:183], v[116:119]
	v_mfma_f32_16x16x32_bf16 v[112:115], v[164:167], v[180:183], v[112:115]
	v_mfma_f32_16x16x32_bf16 v[96:99], v[156:159], v[188:191], v[96:99]
	v_mfma_f32_16x16x32_bf16 v[88:91], v[164:167], v[188:191], v[88:91]
	v_mfma_f32_16x16x32_bf16 v[84:87], v[156:159], v[196:199], v[84:87]
	v_mfma_f32_16x16x32_bf16 v[80:83], v[164:167], v[196:199], v[80:83]
	v_mfma_f32_16x16x32_bf16 v[130:133], v[160:163], v[176:179], v[130:133]
	v_mfma_f32_16x16x32_bf16 v[120:123], v[168:171], v[176:179], v[120:123]
	v_mfma_f32_16x16x32_bf16 v[116:119], v[160:163], v[184:187], v[116:119]
	v_mfma_f32_16x16x32_bf16 v[112:115], v[168:171], v[184:187], v[112:115]
	v_mfma_f32_16x16x32_bf16 v[96:99], v[160:163], v[192:195], v[96:99]
	v_mfma_f32_16x16x32_bf16 v[88:91], v[168:171], v[192:195], v[88:91]
	v_mfma_f32_16x16x32_bf16 v[84:87], v[160:163], v[200:203], v[84:87]
	v_mfma_f32_16x16x32_bf16 v[80:83], v[168:171], v[200:203], v[80:83]
	s_barrier
; #define PG8_STAGE(bufoff, gbase, voff) do { _Pragma("unroll") for (int _i = 0; _i < 2; ++_i) \
;         __builtin_amdgcn_global_load_lds((const unsigned*)((const char*)(gbase) + (voff)[_i]), (PG8_LAS unsigned*)(lds + (bufoff) + ldsw + _i * 8192), 16, 0, 0); } while (0)
; #define PG8_LDA(dst, b, h) do { _Pragma("unroll") for (int m = 0; m < 4; ++m) _Pragma("unroll") for (int k = 0; k < 2; ++k) dst[m][k] = *(const PG8_LAS bf16x8*)(lds + PG8_SA(b, h) + aoff + m * 2048 + k * 1024); } while (0)
; #define PG8_MMA(ai, bj, At, Bt) do { __builtin_amdgcn_s_setprio(1); _Pragma("unroll") for (int m = 0; m < 4; ++m) _Pragma("unroll") for (int n = 0; n < 2; ++n) _Pragma("unroll") for (int k = 0; k < 2; ++k) \
;         acc[ai][bj][m][n] = __builtin_amdgcn_mfma_f32_16x16x32_bf16(Bt[n][k], At[m][k], acc[ai][bj][m][n], 0, 0, 0); __builtin_amdgcn_s_setprio(0); } while (0)
; #define PG8_WAIT_V(n) asm volatile("s_waitcnt vmcnt(" #n ")" ::: "memory")
; #define PG8_WAIT_L(n) asm volatile("s_waitcnt lgkmcnt(" #n ")" ::: "memory")
; #define PG8_BAR __builtin_amdgcn_s_barrier()
; #define PG8_SCHED __builtin_amdgcn_sched_barrier(0)
; template <class Epi, class Sched, bool ALIGN_EPI = false, bool SP2 = false>
; __device__ __forceinline__ void gemm_phase(PG8_LAS unsigned char* lds, const Gemm g, const Sched& S, const Epi& E) {
;     ...
;             PG8_LDA(At, 1, 1); PG8_STAGE(PG8_SB(1, 0), b3, voffB); PG8_STAGE(PG8_SB(1, 1), b3 + hstep, voffB); PG8_STAGE(PG8_SA(1, 0), a3, voffA);
;             PG8_WAIT_V(8); PG8_WAIT_L(0); PG8_BAR; PG8_MMA(1, 0, At, B0); PG8_MMA(1, 1, At, B1); PG8_BAR; PG8_SCHED;
	s_add_i32 s64, s84, s17
	v_lshl_add_u64 v[204:205], v[204:205], 0, s[90:91]
	s_mov_b32 m0, s64
	ds_read_b128 v[172:175], v230 offset:49152
	ds_read_b128 v[176:179], v230 offset:50176
	ds_read_b128 v[180:183], v230 offset:51200
	ds_read_b128 v[184:187], v230 offset:52224
	ds_read_b128 v[188:191], v230 offset:53248
	ds_read_b128 v[192:195], v230 offset:54272
	ds_read_b128 v[196:199], v230 offset:55296
	ds_read_b128 v[200:203], v230 offset:56320
	global_load_lds_dwordx4 v[204:205], off
	s_add_i32 m0, s64, 0x2000
	s_add_u32 s58, s58, 0x40080
	v_lshl_add_u64 v[204:205], v[206:207], 0, s[90:91]
	s_addc_u32 s59, s59, 0
	s_add_i32 s64, s85, s17
	global_load_lds_dwordx4 v[204:205], off
	v_lshl_add_u64 v[204:205], s[58:59], 0, v[128:129]
	s_mov_b32 m0, s64
	s_nop 0
	global_load_lds_dwordx4 v[204:205], off
	v_lshl_add_u64 v[204:205], s[58:59], 0, v[146:147]
	s_add_i32 m0, s64, 0x2000
	s_nop 0
	global_load_lds_dwordx4 v[204:205], off
	v_lshl_add_u64 v[204:205], v[208:209], 0, s[90:91]
	s_mov_b32 m0, s28
	s_nop 0
	global_load_lds_dwordx4 v[204:205], off
	v_lshl_add_u64 v[204:205], v[210:211], 0, s[90:91]
	s_mov_b32 m0, s29
	s_nop 0
	global_load_lds_dwordx4 v[204:205], off
	s_waitcnt vmcnt(8)
	s_waitcnt lgkmcnt(0)
	s_barrier
	s_waitcnt lgkmcnt(0)
	v_mfma_f32_16x16x32_bf16 v[60:63], v[64:67], v[172:175], v[60:63]
	v_mfma_f32_16x16x32_bf16 v[56:59], v[72:75], v[172:175], v[56:59]
	v_mfma_f32_16x16x32_bf16 v[52:55], v[64:67], v[180:183], v[52:55]
	v_mfma_f32_16x16x32_bf16 v[44:47], v[72:75], v[180:183], v[44:47]
	v_mfma_f32_16x16x32_bf16 v[28:31], v[64:67], v[188:191], v[28:31]
	v_mfma_f32_16x16x32_bf16 v[24:27], v[72:75], v[188:191], v[24:27]
	v_mfma_f32_16x16x32_bf16 v[12:15], v[64:67], v[196:199], v[12:15]
	v_mfma_f32_16x16x32_bf16 v[8:11], v[72:75], v[196:199], v[8:11]
	v_mfma_f32_16x16x32_bf16 v[60:63], v[68:71], v[176:179], v[60:63]
	v_mfma_f32_16x16x32_bf16 v[56:59], v[76:79], v[176:179], v[56:59]
	v_mfma_f32_16x16x32_bf16 v[52:55], v[68:71], v[184:187], v[52:55]
	v_mfma_f32_16x16x32_bf16 v[44:47], v[76:79], v[184:187], v[44:47]
	v_mfma_f32_16x16x32_bf16 v[28:31], v[68:71], v[192:195], v[28:31]
	v_mfma_f32_16x16x32_bf16 v[24:27], v[76:79], v[192:195], v[24:27]
	v_mfma_f32_16x16x32_bf16 v[12:15], v[68:71], v[200:203], v[12:15]
	v_mfma_f32_16x16x32_bf16 v[8:11], v[76:79], v[200:203], v[8:11]
	v_mfma_f32_16x16x32_bf16 v[48:51], v[156:159], v[172:175], v[48:51]
	v_mfma_f32_16x16x32_bf16 v[40:43], v[164:167], v[172:175], v[40:43]
	v_mfma_f32_16x16x32_bf16 v[36:39], v[156:159], v[180:183], v[36:39]
	v_mfma_f32_16x16x32_bf16 v[32:35], v[164:167], v[180:183], v[32:35]
	v_mfma_f32_16x16x32_bf16 v[20:23], v[156:159], v[188:191], v[20:23]
	v_mfma_f32_16x16x32_bf16 v[16:19], v[164:167], v[188:191], v[16:19]
	v_mfma_f32_16x16x32_bf16 v[4:7], v[156:159], v[196:199], v[4:7]
	v_mfma_f32_16x16x32_bf16 v[0:3], v[164:167], v[196:199], v[0:3]
	v_mfma_f32_16x16x32_bf16 v[48:51], v[160:163], v[176:179], v[48:51]
	v_mfma_f32_16x16x32_bf16 v[40:43], v[168:171], v[176:179], v[40:43]
	v_mfma_f32_16x16x32_bf16 v[36:39], v[160:163], v[184:187], v[36:39]
	v_mfma_f32_16x16x32_bf16 v[32:35], v[168:171], v[184:187], v[32:35]
	v_mfma_f32_16x16x32_bf16 v[20:23], v[160:163], v[192:195], v[20:23]
	v_mfma_f32_16x16x32_bf16 v[16:19], v[168:171], v[192:195], v[16:19]
	v_mfma_f32_16x16x32_bf16 v[4:7], v[160:163], v[200:203], v[4:7]
	v_mfma_f32_16x16x32_bf16 v[0:3], v[168:171], v[200:203], v[0:3]
	s_barrier
	s_add_i32 s94, s94, 2
	s_add_u32 vcc_lo, vcc_lo, 0x100
	s_addc_u32 vcc_hi, vcc_hi, 0
	s_add_u32 s88, s88, 0x100
	s_addc_u32 s93, s93, 0
	s_cmp_gt_u32 s94, 13
	s_cbranch_scc0 .LBB0_598
	s_and_b64 vcc, exec, s[72:73]
	s_cbranch_vccz .LBB0_601
	s_barrier

; #define PG8_STAGE(bufoff, gbase, voff) do { _Pragma("unroll") for (int _i = 0; _i < 2; ++_i) \
;         __builtin_amdgcn_global_load_lds((const unsigned*)((const char*)(gbase) + (voff)[_i]), (PG8_LAS unsigned*)(lds + (bufoff) + ldsw + _i * 8192), 16, 0, 0); } while (0)
; #define PG8_LDA(dst, b, h) do { _Pragma("unroll") for (int m = 0; m < 4; ++m) _Pragma("unroll") for (int k = 0; k < 2; ++k) dst[m][k] = *(const PG8_LAS bf16x8*)(lds + PG8_SA(b, h) + aoff + m * 2048 + k * 1024); } while (0)
; #define PG8_LDB(dst, b, h) do { _Pragma("unroll") for (int n = 0; n < 2; ++n) _Pragma("unroll") for (int k = 0; k < 2; ++k) dst[n][k] = *(const PG8_LAS bf16x8*)(lds + PG8_SB(b, h) + boff + n * 2048 + k * 1024); } while (0)
; #define PG8_MMA(ai, bj, At, Bt) do { __builtin_amdgcn_s_setprio(1); _Pragma("unroll") for (int m = 0; m < 4; ++m) _Pragma("unroll") for (int n = 0; n < 2; ++n) _Pragma("unroll") for (int k = 0; k < 2; ++k) \
;         acc[ai][bj][m][n] = __builtin_amdgcn_mfma_f32_16x16x32_bf16(Bt[n][k], At[m][k], acc[ai][bj][m][n], 0, 0, 0); __builtin_amdgcn_s_setprio(0); } while (0)
; #define PG8_WAIT_V(n) asm volatile("s_waitcnt vmcnt(" #n ")" ::: "memory")
; #define PG8_BAR __builtin_amdgcn_s_barrier()
; template <class Epi, class Sched, bool ALIGN_EPI = false, bool SP2 = false>
; __device__ __forceinline__ void gemm_phase(PG8_LAS unsigned char* lds, const Gemm g, const Sched& S, const Epi& E) {
;     ...
;         for (int t = 0; t < nt; t += 2) {
;             const bool last = (t == nt - 2);
;             const char* a1 = cA + (size_t)(t + 1) * kstep;
;             const char* a2 = last ? nA : cA + (size_t)(t + 2) * kstep; const char* b2 = last ? nB : cB + (size_t)(t + 2) * kstep;
;             const char* a3 = a2 + kstep; const char* b3 = b2 + kstep;
;             if (last && has_next) S.a_ready(nxt);
;             if constexpr (SP2) {
;             PG8_LDB(B0, 0, 0); PG8_LDB(B1, 0, 1); PG8_SCHED; PG8_LDA(At, 0, 0); PG8_STAGE(PG8_SA(1, 1), a1 + hstep, voffA);
;             PG8_WAIT_V(8); PG8_WAIT_L(0); PG8_BAR; PG8_MMA(0, 0, At, B0); PG8_MMA(0, 1, At, B1); PG8_BAR; PG8_SCHED;
;             PG8_LDA(At, 0, 1); PG8_STAGE(PG8_SB(0, 0), b2, voffB); PG8_STAGE(PG8_SB(0, 1), b2 + hstep, voffB); PG8_STAGE(PG8_SA(0, 0), a2, voffA);
;             PG8_WAIT_V(8); PG8_WAIT_L(0); PG8_BAR; PG8_MMA(1, 0, At, B0); PG8_MMA(1, 1, At, B1); PG8_BAR; PG8_SCHED;
.LBB0_813:
	s_add_u32 s8, s66, 0xfffc0080
	s_addc_u32 s37, s67, -1
	s_add_i32 s49, 0, 0x10000
	s_cmp_eq_u32 s36, 12
	s_cselect_b32 s65, s28, s37
	s_cselect_b32 s64, s29, s8
	s_cselect_b32 s59, s30, s35
	s_cselect_b32 s58, s31, s34
	s_add_i32 s8, 0, 0x14000
	v_add_u32_e32 v156, s49, v145
	v_add_u32_e32 v172, s8, v145
	ds_read_b128 v[140:143], v156
	ds_read_b128 v[148:151], v156 offset:1024
	ds_read_b128 v[152:155], v156 offset:2048
	ds_read_b128 v[156:159], v156 offset:3072
	ds_read_b128 v[160:163], v172
	ds_read_b128 v[164:167], v172 offset:1024
	ds_read_b128 v[168:171], v172 offset:2048
	ds_read_b128 v[172:175], v172 offset:3072
	v_lshl_add_u64 v[208:209], s[66:67], 0, v[136:137]
	s_add_i32 m0, s18, 0xc000
	ds_read_b128 v[176:179], v147
	ds_read_b128 v[180:183], v147 offset:1024
	ds_read_b128 v[184:187], v147 offset:2048
	ds_read_b128 v[188:191], v147 offset:3072
	ds_read_b128 v[192:195], v147 offset:4096
	ds_read_b128 v[196:199], v147 offset:5120
	ds_read_b128 v[200:203], v147 offset:6144
	ds_read_b128 v[204:207], v147 offset:7168
	global_load_lds_dwordx4 v[208:209], off
	v_lshl_add_u64 v[208:209], s[66:67], 0, v[138:139]
	s_add_i32 m0, s18, 0xe000
	s_nop 0
	global_load_lds_dwordx4 v[208:209], off
	s_waitcnt vmcnt(8)
	s_waitcnt lgkmcnt(0)
	s_barrier
	s_waitcnt lgkmcnt(0)
	v_mfma_f32_16x16x32_bf16 v[124:127], v[140:143], v[176:179], v[124:127]
	v_mfma_f32_16x16x32_bf16 v[116:119], v[152:155], v[176:179], v[116:119]
	v_mfma_f32_16x16x32_bf16 v[108:111], v[140:143], v[184:187], v[108:111]
	v_mfma_f32_16x16x32_bf16 v[100:103], v[152:155], v[184:187], v[100:103]
	v_mfma_f32_16x16x32_bf16 v[92:95], v[140:143], v[192:195], v[92:95]
	v_mfma_f32_16x16x32_bf16 v[84:87], v[152:155], v[192:195], v[84:87]
	v_mfma_f32_16x16x32_bf16 v[76:79], v[140:143], v[200:203], v[76:79]
	v_mfma_f32_16x16x32_bf16 v[68:71], v[152:155], v[200:203], v[68:71]
	v_mfma_f32_16x16x32_bf16 v[124:127], v[148:151], v[180:183], v[124:127]
	v_mfma_f32_16x16x32_bf16 v[116:119], v[156:159], v[180:183], v[116:119]
	v_mfma_f32_16x16x32_bf16 v[108:111], v[148:151], v[188:191], v[108:111]
	v_mfma_f32_16x16x32_bf16 v[100:103], v[156:159], v[188:191], v[100:103]
	v_mfma_f32_16x16x32_bf16 v[92:95], v[148:151], v[196:199], v[92:95]
	v_mfma_f32_16x16x32_bf16 v[84:87], v[156:159], v[196:199], v[84:87]
	v_mfma_f32_16x16x32_bf16 v[76:79], v[148:151], v[204:207], v[76:79]
	v_mfma_f32_16x16x32_bf16 v[68:71], v[156:159], v[204:207], v[68:71]
	v_mfma_f32_16x16x32_bf16 v[120:123], v[160:163], v[176:179], v[120:123]
	v_mfma_f32_16x16x32_bf16 v[112:115], v[168:171], v[176:179], v[112:115]
	v_mfma_f32_16x16x32_bf16 v[104:107], v[160:163], v[184:187], v[104:107]
	v_mfma_f32_16x16x32_bf16 v[96:99], v[168:171], v[184:187], v[96:99]
	v_mfma_f32_16x16x32_bf16 v[88:91], v[160:163], v[192:195], v[88:91]
	v_mfma_f32_16x16x32_bf16 v[80:83], v[168:171], v[192:195], v[80:83]
	v_mfma_f32_16x16x32_bf16 v[72:75], v[160:163], v[200:203], v[72:75]
	v_mfma_f32_16x16x32_bf16 v[64:67], v[168:171], v[200:203], v[64:67]
	v_mfma_f32_16x16x32_bf16 v[120:123], v[164:167], v[180:183], v[120:123]
	v_mfma_f32_16x16x32_bf16 v[112:115], v[172:175], v[180:183], v[112:115]
	v_mfma_f32_16x16x32_bf16 v[104:107], v[164:167], v[188:191], v[104:107]
	v_mfma_f32_16x16x32_bf16 v[96:99], v[172:175], v[188:191], v[96:99]
	v_mfma_f32_16x16x32_bf16 v[88:91], v[164:167], v[196:199], v[88:91]
	v_mfma_f32_16x16x32_bf16 v[80:83], v[172:175], v[196:199], v[80:83]
	v_mfma_f32_16x16x32_bf16 v[72:75], v[164:167], v[204:207], v[72:75]
	v_mfma_f32_16x16x32_bf16 v[64:67], v[172:175], v[204:207], v[64:67]
	s_barrier
	s_add_i32 s37, s49, s17
	v_lshl_add_u64 v[208:209], s[58:59], 0, v[128:129]
	s_mov_b32 m0, s37
	ds_read_b128 v[176:179], v147 offset:16384
	ds_read_b128 v[180:183], v147 offset:17408
	ds_read_b128 v[184:187], v147 offset:18432
	ds_read_b128 v[188:191], v147 offset:19456
	ds_read_b128 v[192:195], v147 offset:20480
	ds_read_b128 v[196:199], v147 offset:21504
	ds_read_b128 v[200:203], v147 offset:22528
	ds_read_b128 v[204:207], v147 offset:23552
	global_load_lds_dwordx4 v[208:209], off
	s_add_i32 m0, s37, 0x2000
	s_add_u32 s72, s58, 0x40000
	v_lshl_add_u64 v[210:211], s[58:59], 0, v[130:131]
	s_addc_u32 s73, s59, 0
	s_add_i32 s8, s8, s17
	global_load_lds_dwordx4 v[210:211], off
	v_lshl_add_u64 v[214:215], s[72:73], 0, v[128:129]
	s_mov_b32 m0, s8
	v_lshl_add_u64 v[222:223], s[64:65], 0, v[132:133]
	global_load_lds_dwordx4 v[214:215], off
	v_lshl_add_u64 v[214:215], s[72:73], 0, v[130:131]
	s_add_i32 m0, s8, 0x2000
	s_nop 0
	global_load_lds_dwordx4 v[214:215], off
	v_lshl_add_u64 v[214:215], s[64:65], 0, v[134:135]
	s_mov_b32 m0, s18
	s_nop 0
	global_load_lds_dwordx4 v[214:215], off
	s_mov_b32 m0, s19
	s_nop 0
	global_load_lds_dwordx4 v[222:223], off
	s_waitcnt vmcnt(8)
	s_waitcnt lgkmcnt(0)
	s_barrier
; #define PG8_STAGE(bufoff, gbase, voff) do { _Pragma("unroll") for (int _i = 0; _i < 2; ++_i) \
;         __builtin_amdgcn_global_load_lds((const unsigned*)((const char*)(gbase) + (voff)[_i]), (PG8_LAS unsigned*)(lds + (bufoff) + ldsw + _i * 8192), 16, 0, 0); } while (0)
; #define PG8_LDA(dst, b, h) do { _Pragma("unroll") for (int m = 0; m < 4; ++m) _Pragma("unroll") for (int k = 0; k < 2; ++k) dst[m][k] = *(const PG8_LAS bf16x8*)(lds + PG8_SA(b, h) + aoff + m * 2048 + k * 1024); } while (0)
; #define PG8_LDB(dst, b, h) do { _Pragma("unroll") for (int n = 0; n < 2; ++n) _Pragma("unroll") for (int k = 0; k < 2; ++k) dst[n][k] = *(const PG8_LAS bf16x8*)(lds + PG8_SB(b, h) + boff + n * 2048 + k * 1024); } while (0)
; #define PG8_MMA(ai, bj, At, Bt) do { __builtin_amdgcn_s_setprio(1); _Pragma("unroll") for (int m = 0; m < 4; ++m) _Pragma("unroll") for (int n = 0; n < 2; ++n) _Pragma("unroll") for (int k = 0; k < 2; ++k) \
;         acc[ai][bj][m][n] = __builtin_amdgcn_mfma_f32_16x16x32_bf16(Bt[n][k], At[m][k], acc[ai][bj][m][n], 0, 0, 0); __builtin_amdgcn_s_setprio(0); } while (0)
; #define PG8_WAIT_V(n) asm volatile("s_waitcnt vmcnt(" #n ")" ::: "memory")
; #define PG8_WAIT_L(n) asm volatile("s_waitcnt lgkmcnt(" #n ")" ::: "memory")
; #define PG8_BAR __builtin_amdgcn_s_barrier()
; #define PG8_SCHED __builtin_amdgcn_sched_barrier(0)
; template <class Epi, class Sched, bool ALIGN_EPI = false, bool SP2 = false>
; __device__ __forceinline__ void gemm_phase(PG8_LAS unsigned char* lds, const Gemm g, const Sched& S, const Epi& E) {
;     ...
;             PG8_WAIT_V(8); PG8_WAIT_L(0); PG8_BAR; PG8_MMA(1, 0, At, B0); PG8_MMA(1, 1, At, B1); PG8_BAR; PG8_SCHED;
;             PG8_LDB(B0, 1, 0); PG8_LDB(B1, 1, 1); PG8_SCHED; PG8_LDA(At, 1, 0); PG8_STAGE(PG8_SA(0, 1), a2 + hstep, voffA);
;             PG8_WAIT_V(8); PG8_WAIT_L(0); PG8_BAR; PG8_MMA(0, 0, At, B0); PG8_MMA(0, 1, At, B1); PG8_BAR; PG8_SCHED;
	s_waitcnt lgkmcnt(0)
	v_mfma_f32_16x16x32_bf16 v[60:63], v[140:143], v[176:179], v[60:63]
	v_mfma_f32_16x16x32_bf16 v[52:55], v[152:155], v[176:179], v[52:55]
	v_mfma_f32_16x16x32_bf16 v[44:47], v[140:143], v[184:187], v[44:47]
	v_mfma_f32_16x16x32_bf16 v[36:39], v[152:155], v[184:187], v[36:39]
	v_mfma_f32_16x16x32_bf16 v[28:31], v[140:143], v[192:195], v[28:31]
	v_mfma_f32_16x16x32_bf16 v[20:23], v[152:155], v[192:195], v[20:23]
	v_mfma_f32_16x16x32_bf16 v[12:15], v[140:143], v[200:203], v[12:15]
	v_mfma_f32_16x16x32_bf16 v[4:7], v[152:155], v[200:203], v[4:7]
	v_mfma_f32_16x16x32_bf16 v[60:63], v[148:151], v[180:183], v[60:63]
	v_mfma_f32_16x16x32_bf16 v[52:55], v[156:159], v[180:183], v[52:55]
	v_mfma_f32_16x16x32_bf16 v[44:47], v[148:151], v[188:191], v[44:47]
	v_mfma_f32_16x16x32_bf16 v[36:39], v[156:159], v[188:191], v[36:39]
	v_mfma_f32_16x16x32_bf16 v[28:31], v[148:151], v[196:199], v[28:31]
	v_mfma_f32_16x16x32_bf16 v[20:23], v[156:159], v[196:199], v[20:23]
	v_mfma_f32_16x16x32_bf16 v[12:15], v[148:151], v[204:207], v[12:15]
	v_mfma_f32_16x16x32_bf16 v[4:7], v[156:159], v[204:207], v[4:7]
	v_mfma_f32_16x16x32_bf16 v[56:59], v[160:163], v[176:179], v[56:59]
	v_mfma_f32_16x16x32_bf16 v[48:51], v[168:171], v[176:179], v[48:51]
	v_mfma_f32_16x16x32_bf16 v[40:43], v[160:163], v[184:187], v[40:43]
	v_mfma_f32_16x16x32_bf16 v[32:35], v[168:171], v[184:187], v[32:35]
	v_mfma_f32_16x16x32_bf16 v[24:27], v[160:163], v[192:195], v[24:27]
	v_mfma_f32_16x16x32_bf16 v[16:19], v[168:171], v[192:195], v[16:19]
	v_mfma_f32_16x16x32_bf16 v[8:11], v[160:163], v[200:203], v[8:11]
	v_mfma_f32_16x16x32_bf16 v[0:3], v[168:171], v[200:203], v[0:3]
	v_mfma_f32_16x16x32_bf16 v[56:59], v[164:167], v[180:183], v[56:59]
	v_mfma_f32_16x16x32_bf16 v[48:51], v[172:175], v[180:183], v[48:51]
	v_mfma_f32_16x16x32_bf16 v[40:43], v[164:167], v[188:191], v[40:43]
	v_mfma_f32_16x16x32_bf16 v[32:35], v[172:175], v[188:191], v[32:35]
	v_mfma_f32_16x16x32_bf16 v[24:27], v[164:167], v[196:199], v[24:27]
	v_mfma_f32_16x16x32_bf16 v[16:19], v[172:175], v[196:199], v[16:19]
	v_mfma_f32_16x16x32_bf16 v[8:11], v[164:167], v[204:207], v[8:11]
	v_mfma_f32_16x16x32_bf16 v[0:3], v[172:175], v[204:207], v[0:3]
	s_barrier
	s_add_i32 s8, 0, 0x18000
	s_add_i32 s37, 0, 0x1c000
	v_add_u32_e32 v156, s8, v145
	v_add_u32_e32 v172, s37, v145
	ds_read_b128 v[140:143], v156
	ds_read_b128 v[148:151], v156 offset:1024
	ds_read_b128 v[152:155], v156 offset:2048
	ds_read_b128 v[156:159], v156 offset:3072
	ds_read_b128 v[160:163], v172
	ds_read_b128 v[164:167], v172 offset:1024
	ds_read_b128 v[168:171], v172 offset:2048
	ds_read_b128 v[172:175], v172 offset:3072
	s_add_u32 s64, s64, 0x40000
	s_addc_u32 s65, s65, 0
	s_mov_b32 m0, s20
	v_lshl_add_u64 v[228:229], s[64:65], 0, v[134:135]
	ds_read_b128 v[176:179], v147 offset:32768
	ds_read_b128 v[180:183], v147 offset:33792
	ds_read_b128 v[184:187], v147 offset:34816
	ds_read_b128 v[188:191], v147 offset:35840
	ds_read_b128 v[192:195], v147 offset:36864
	ds_read_b128 v[196:199], v147 offset:37888
	ds_read_b128 v[200:203], v147 offset:38912
	ds_read_b128 v[204:207], v147 offset:39936
	global_load_lds_dwordx4 v[228:229], off
	v_lshl_add_u64 v[228:229], s[64:65], 0, v[132:133]
	s_mov_b32 m0, s21
	s_nop 0
	global_load_lds_dwordx4 v[228:229], off
	s_waitcnt vmcnt(8)
	s_waitcnt lgkmcnt(0)
	s_barrier
	s_waitcnt lgkmcnt(0)
	v_mfma_f32_16x16x32_bf16 v[124:127], v[140:143], v[176:179], v[124:127]
	v_mfma_f32_16x16x32_bf16 v[116:119], v[152:155], v[176:179], v[116:119]
	v_mfma_f32_16x16x32_bf16 v[108:111], v[140:143], v[184:187], v[108:111]
	v_mfma_f32_16x16x32_bf16 v[100:103], v[152:155], v[184:187], v[100:103]
	v_mfma_f32_16x16x32_bf16 v[92:95], v[140:143], v[192:195], v[92:95]
	v_mfma_f32_16x16x32_bf16 v[84:87], v[152:155], v[192:195], v[84:87]
	v_mfma_f32_16x16x32_bf16 v[76:79], v[140:143], v[200:203], v[76:79]
	v_mfma_f32_16x16x32_bf16 v[68:71], v[152:155], v[200:203], v[68:71]
	v_mfma_f32_16x16x32_bf16 v[124:127], v[148:151], v[180:183], v[124:127]
	v_mfma_f32_16x16x32_bf16 v[116:119], v[156:159], v[180:183], v[116:119]
	v_mfma_f32_16x16x32_bf16 v[108:111], v[148:151], v[188:191], v[108:111]
	v_mfma_f32_16x16x32_bf16 v[100:103], v[156:159], v[188:191], v[100:103]
	v_mfma_f32_16x16x32_bf16 v[92:95], v[148:151], v[196:199], v[92:95]
	v_mfma_f32_16x16x32_bf16 v[84:87], v[156:159], v[196:199], v[84:87]
	v_mfma_f32_16x16x32_bf16 v[76:79], v[148:151], v[204:207], v[76:79]
	v_mfma_f32_16x16x32_bf16 v[68:71], v[156:159], v[204:207], v[68:71]
	v_mfma_f32_16x16x32_bf16 v[120:123], v[160:163], v[176:179], v[120:123]
	v_mfma_f32_16x16x32_bf16 v[112:115], v[168:171], v[176:179], v[112:115]
	v_mfma_f32_16x16x32_bf16 v[104:107], v[160:163], v[184:187], v[104:107]
	v_mfma_f32_16x16x32_bf16 v[96:99], v[168:171], v[184:187], v[96:99]
	v_mfma_f32_16x16x32_bf16 v[88:91], v[160:163], v[192:195], v[88:91]
	v_mfma_f32_16x16x32_bf16 v[80:83], v[168:171], v[192:195], v[80:83]
	v_mfma_f32_16x16x32_bf16 v[72:75], v[160:163], v[200:203], v[72:75]
	v_mfma_f32_16x16x32_bf16 v[64:67], v[168:171], v[200:203], v[64:67]
	v_mfma_f32_16x16x32_bf16 v[120:123], v[164:167], v[180:183], v[120:123]
	v_mfma_f32_16x16x32_bf16 v[112:115], v[172:175], v[180:183], v[112:115]
	v_mfma_f32_16x16x32_bf16 v[104:107], v[164:167], v[188:191], v[104:107]
	v_mfma_f32_16x16x32_bf16 v[96:99], v[172:175], v[188:191], v[96:99]
	v_mfma_f32_16x16x32_bf16 v[88:91], v[164:167], v[196:199], v[88:91]
	v_mfma_f32_16x16x32_bf16 v[80:83], v[172:175], v[196:199], v[80:83]
	v_mfma_f32_16x16x32_bf16 v[72:75], v[164:167], v[204:207], v[72:75]
	v_mfma_f32_16x16x32_bf16 v[64:67], v[172:175], v[204:207], v[64:67]
	s_barrier
; #define PG8_STAGE(bufoff, gbase, voff) do { _Pragma("unroll") for (int _i = 0; _i < 2; ++_i) \
;         __builtin_amdgcn_global_load_lds((const unsigned*)((const char*)(gbase) + (voff)[_i]), (PG8_LAS unsigned*)(lds + (bufoff) + ldsw + _i * 8192), 16, 0, 0); } while (0)
; #define PG8_LDA(dst, b, h) do { _Pragma("unroll") for (int m = 0; m < 4; ++m) _Pragma("unroll") for (int k = 0; k < 2; ++k) dst[m][k] = *(const PG8_LAS bf16x8*)(lds + PG8_SA(b, h) + aoff + m * 2048 + k * 1024); } while (0)
; #define PG8_MMA(ai, bj, At, Bt) do { __builtin_amdgcn_s_setprio(1); _Pragma("unroll") for (int m = 0; m < 4; ++m) _Pragma("unroll") for (int n = 0; n < 2; ++n) _Pragma("unroll") for (int k = 0; k < 2; ++k) \
;         acc[ai][bj][m][n] = __builtin_amdgcn_mfma_f32_16x16x32_bf16(Bt[n][k], At[m][k], acc[ai][bj][m][n], 0, 0, 0); __builtin_amdgcn_s_setprio(0); } while (0)
; #define PG8_WAIT_V(n) asm volatile("s_waitcnt vmcnt(" #n ")" ::: "memory")
; #define PG8_WAIT_L(n) asm volatile("s_waitcnt lgkmcnt(" #n ")" ::: "memory")
; #define PG8_BAR __builtin_amdgcn_s_barrier()
; #define PG8_SCHED __builtin_amdgcn_sched_barrier(0)
; template <class Epi, class Sched, bool ALIGN_EPI = false, bool SP2 = false>
; __device__ __forceinline__ void gemm_phase(PG8_LAS unsigned char* lds, const Gemm g, const Sched& S, const Epi& E) {
;     ...
;             PG8_LDA(At, 1, 1); PG8_STAGE(PG8_SB(1, 0), b3, voffB); PG8_STAGE(PG8_SB(1, 1), b3 + hstep, voffB); PG8_STAGE(PG8_SA(1, 0), a3, voffA);
;             PG8_WAIT_V(8); PG8_WAIT_L(0); PG8_BAR; PG8_MMA(1, 0, At, B0); PG8_MMA(1, 1, At, B1); PG8_BAR; PG8_SCHED;
	s_add_i32 s8, s8, s17
	v_lshl_add_u64 v[208:209], v[208:209], 0, s[90:91]
	s_mov_b32 m0, s8
	ds_read_b128 v[176:179], v147 offset:49152
	ds_read_b128 v[180:183], v147 offset:50176
	ds_read_b128 v[184:187], v147 offset:51200
	ds_read_b128 v[188:191], v147 offset:52224
	ds_read_b128 v[192:195], v147 offset:53248
	ds_read_b128 v[196:199], v147 offset:54272
	ds_read_b128 v[200:203], v147 offset:55296
	ds_read_b128 v[204:207], v147 offset:56320
	global_load_lds_dwordx4 v[208:209], off
	s_add_i32 m0, s8, 0x2000
	s_add_u32 s58, s58, 0x40080
	v_lshl_add_u64 v[208:209], v[210:211], 0, s[90:91]
	s_addc_u32 s59, s59, 0
	s_add_i32 s8, s37, s17
	global_load_lds_dwordx4 v[208:209], off
	v_lshl_add_u64 v[208:209], s[58:59], 0, v[128:129]
	s_mov_b32 m0, s8
	s_nop 0
	global_load_lds_dwordx4 v[208:209], off
	v_lshl_add_u64 v[208:209], s[58:59], 0, v[130:131]
	s_add_i32 m0, s8, 0x2000
	s_nop 0
	global_load_lds_dwordx4 v[208:209], off
	v_lshl_add_u64 v[208:209], v[214:215], 0, s[90:91]
	s_mov_b32 m0, s22
	s_nop 0
	global_load_lds_dwordx4 v[208:209], off
	v_lshl_add_u64 v[208:209], v[222:223], 0, s[90:91]
	s_mov_b32 m0, s23
	s_nop 0
	global_load_lds_dwordx4 v[208:209], off
	s_waitcnt vmcnt(8)
	s_waitcnt lgkmcnt(0)
	s_barrier
	s_waitcnt lgkmcnt(0)
	v_mfma_f32_16x16x32_bf16 v[60:63], v[140:143], v[176:179], v[60:63]
	v_mfma_f32_16x16x32_bf16 v[52:55], v[152:155], v[176:179], v[52:55]
	v_mfma_f32_16x16x32_bf16 v[44:47], v[140:143], v[184:187], v[44:47]
	v_mfma_f32_16x16x32_bf16 v[36:39], v[152:155], v[184:187], v[36:39]
	v_mfma_f32_16x16x32_bf16 v[28:31], v[140:143], v[192:195], v[28:31]
	v_mfma_f32_16x16x32_bf16 v[20:23], v[152:155], v[192:195], v[20:23]
	v_mfma_f32_16x16x32_bf16 v[12:15], v[140:143], v[200:203], v[12:15]
	v_mfma_f32_16x16x32_bf16 v[4:7], v[152:155], v[200:203], v[4:7]
	v_mfma_f32_16x16x32_bf16 v[60:63], v[148:151], v[180:183], v[60:63]
	v_mfma_f32_16x16x32_bf16 v[52:55], v[156:159], v[180:183], v[52:55]
	v_mfma_f32_16x16x32_bf16 v[44:47], v[148:151], v[188:191], v[44:47]
	v_mfma_f32_16x16x32_bf16 v[36:39], v[156:159], v[188:191], v[36:39]
	v_mfma_f32_16x16x32_bf16 v[28:31], v[148:151], v[196:199], v[28:31]
	v_mfma_f32_16x16x32_bf16 v[20:23], v[156:159], v[196:199], v[20:23]
	v_mfma_f32_16x16x32_bf16 v[12:15], v[148:151], v[204:207], v[12:15]
	v_mfma_f32_16x16x32_bf16 v[4:7], v[156:159], v[204:207], v[4:7]
	v_mfma_f32_16x16x32_bf16 v[56:59], v[160:163], v[176:179], v[56:59]
	v_mfma_f32_16x16x32_bf16 v[48:51], v[168:171], v[176:179], v[48:51]
	v_mfma_f32_16x16x32_bf16 v[40:43], v[160:163], v[184:187], v[40:43]
	v_mfma_f32_16x16x32_bf16 v[32:35], v[168:171], v[184:187], v[32:35]
	v_mfma_f32_16x16x32_bf16 v[24:27], v[160:163], v[192:195], v[24:27]
	v_mfma_f32_16x16x32_bf16 v[16:19], v[168:171], v[192:195], v[16:19]
	v_mfma_f32_16x16x32_bf16 v[8:11], v[160:163], v[200:203], v[8:11]
	v_mfma_f32_16x16x32_bf16 v[0:3], v[168:171], v[200:203], v[0:3]
	v_mfma_f32_16x16x32_bf16 v[56:59], v[164:167], v[180:183], v[56:59]
	v_mfma_f32_16x16x32_bf16 v[48:51], v[172:175], v[180:183], v[48:51]
	v_mfma_f32_16x16x32_bf16 v[40:43], v[164:167], v[188:191], v[40:43]
	v_mfma_f32_16x16x32_bf16 v[32:35], v[172:175], v[188:191], v[32:35]
	v_mfma_f32_16x16x32_bf16 v[24:27], v[164:167], v[196:199], v[24:27]
	v_mfma_f32_16x16x32_bf16 v[16:19], v[172:175], v[196:199], v[16:19]
	v_mfma_f32_16x16x32_bf16 v[8:11], v[164:167], v[204:207], v[8:11]
	v_mfma_f32_16x16x32_bf16 v[0:3], v[172:175], v[204:207], v[0:3]
	s_barrier
	s_add_i32 s36, s36, 2
	s_add_u32 s66, s66, 0x100
	s_addc_u32 s67, s67, 0
	s_add_u32 s34, s34, 0x100
	s_addc_u32 s35, s35, 0
	s_cmp_gt_u32 s36, 13
	s_cbranch_scc0 .LBB0_813
	s_and_b64 vcc, exec, s[46:47]
	s_cbranch_vccz .LBB0_816
	s_barrier

; #define PG8_STAGE(bufoff, gbase, voff) do { _Pragma("unroll") for (int _i = 0; _i < 2; ++_i) \
;         __builtin_amdgcn_global_load_lds((const unsigned*)((const char*)(gbase) + (voff)[_i]), (PG8_LAS unsigned*)(lds + (bufoff) + ldsw + _i * 8192), 16, 0, 0); } while (0)
; #define PG8_LDA(dst, b, h) do { _Pragma("unroll") for (int m = 0; m < 4; ++m) _Pragma("unroll") for (int k = 0; k < 2; ++k) dst[m][k] = *(const PG8_LAS bf16x8*)(lds + PG8_SA(b, h) + aoff + m * 2048 + k * 1024); } while (0)
; #define PG8_LDB(dst, b, h) do { _Pragma("unroll") for (int n = 0; n < 2; ++n) _Pragma("unroll") for (int k = 0; k < 2; ++k) dst[n][k] = *(const PG8_LAS bf16x8*)(lds + PG8_SB(b, h) + boff + n * 2048 + k * 1024); } while (0)
; #define PG8_MMA(ai, bj, At, Bt) do { __builtin_amdgcn_s_setprio(1); _Pragma("unroll") for (int m = 0; m < 4; ++m) _Pragma("unroll") for (int n = 0; n < 2; ++n) _Pragma("unroll") for (int k = 0; k < 2; ++k) \
;         acc[ai][bj][m][n] = __builtin_amdgcn_mfma_f32_16x16x32_bf16(Bt[n][k], At[m][k], acc[ai][bj][m][n], 0, 0, 0); __builtin_amdgcn_s_setprio(0); } while (0)
; #define PG8_WAIT_V(n) asm volatile("s_waitcnt vmcnt(" #n ")" ::: "memory")
; #define PG8_BAR __builtin_amdgcn_s_barrier()
; template <class Epi, class Sched, bool ALIGN_EPI = false, bool SP2 = false>
; __device__ __forceinline__ void gemm_phase(PG8_LAS unsigned char* lds, const Gemm g, const Sched& S, const Epi& E) {
;     ...
;         for (int t = 0; t < nt; t += 2) {
;             const bool last = (t == nt - 2);
;             const char* a1 = cA + (size_t)(t + 1) * kstep;
;             const char* a2 = last ? nA : cA + (size_t)(t + 2) * kstep; const char* b2 = last ? nB : cB + (size_t)(t + 2) * kstep;
;             const char* a3 = a2 + kstep; const char* b3 = b2 + kstep;
;             if (last && has_next) S.a_ready(nxt);
;             if constexpr (SP2) {
;             PG8_LDB(B0, 0, 0); PG8_LDB(B1, 0, 1); PG8_SCHED; PG8_LDA(At, 0, 0); PG8_STAGE(PG8_SA(1, 1), a1 + hstep, voffA);
;             PG8_WAIT_V(8); PG8_WAIT_L(0); PG8_BAR; PG8_MMA(0, 0, At, B0); PG8_MMA(0, 1, At, B1); PG8_BAR; PG8_SCHED;
;             PG8_LDA(At, 0, 1); PG8_STAGE(PG8_SB(0, 0), b2, voffB); PG8_STAGE(PG8_SB(0, 1), b2 + hstep, voffB); PG8_STAGE(PG8_SA(0, 0), a2, voffA);
;             PG8_WAIT_V(8); PG8_WAIT_L(0); PG8_BAR; PG8_MMA(1, 0, At, B0); PG8_MMA(1, 1, At, B1); PG8_BAR; PG8_SCHED;
.LBB0_957:
	s_add_u32 s44, s96, 0x100
	s_addc_u32 s45, s97, 0
	s_add_i32 s8, 0, 0x10000
	s_cmp_eq_u32 s70, 40
	s_cselect_b32 s65, s67, s45
	s_cselect_b32 s64, s66, s44
	s_cselect_b32 s47, s73, s37
	s_cselect_b32 s46, s72, s36
	s_add_i32 s88, 0, 0x14000
	v_add_u32_e32 v142, s8, v185
	v_add_u32_e32 v168, s88, v185
	ds_read_b128 v[130:133], v142
	ds_read_b128 v[134:137], v142 offset:1024
	ds_read_b128 v[138:141], v142 offset:2048
	ds_read_b128 v[142:145], v142 offset:3072
	ds_read_b128 v[156:159], v168
	ds_read_b128 v[160:163], v168 offset:1024
	ds_read_b128 v[164:167], v168 offset:2048
	ds_read_b128 v[168:171], v168 offset:3072
	v_lshl_add_u64 v[208:209], s[96:97], 0, v[152:153]
	s_add_i32 m0, s15, 0xc000
	ds_read_b128 v[172:175], v191
	ds_read_b128 v[176:179], v191 offset:1024
	ds_read_b128 v[180:183], v191 offset:2048
	ds_read_b128 v[186:189], v191 offset:3072
	ds_read_b128 v[192:195], v191 offset:4096
	ds_read_b128 v[196:199], v191 offset:5120
	ds_read_b128 v[200:203], v191 offset:6144
	ds_read_b128 v[204:207], v191 offset:7168
	global_load_lds_dwordx4 v[208:209], off
	v_lshl_add_u64 v[208:209], s[96:97], 0, v[154:155]
	s_add_i32 m0, s15, 0xe000
	s_nop 0
	global_load_lds_dwordx4 v[208:209], off
	s_waitcnt vmcnt(8)
	s_waitcnt lgkmcnt(0)
	s_barrier
	s_waitcnt lgkmcnt(0)
	v_mfma_f32_16x16x32_bf16 v[124:127], v[130:133], v[172:175], v[124:127]
	v_mfma_f32_16x16x32_bf16 v[120:123], v[138:141], v[172:175], v[120:123]
	v_mfma_f32_16x16x32_bf16 v[108:111], v[130:133], v[180:183], v[108:111]
	v_mfma_f32_16x16x32_bf16 v[104:107], v[138:141], v[180:183], v[104:107]
	v_mfma_f32_16x16x32_bf16 v[92:95], v[130:133], v[192:195], v[92:95]
	v_mfma_f32_16x16x32_bf16 v[88:91], v[138:141], v[192:195], v[88:91]
	v_mfma_f32_16x16x32_bf16 v[76:79], v[130:133], v[200:203], v[76:79]
	v_mfma_f32_16x16x32_bf16 v[72:75], v[138:141], v[200:203], v[72:75]
	v_mfma_f32_16x16x32_bf16 v[124:127], v[134:137], v[176:179], v[124:127]
	v_mfma_f32_16x16x32_bf16 v[120:123], v[142:145], v[176:179], v[120:123]
	v_mfma_f32_16x16x32_bf16 v[108:111], v[134:137], v[186:189], v[108:111]
	v_mfma_f32_16x16x32_bf16 v[104:107], v[142:145], v[186:189], v[104:107]
	v_mfma_f32_16x16x32_bf16 v[92:95], v[134:137], v[196:199], v[92:95]
	v_mfma_f32_16x16x32_bf16 v[88:91], v[142:145], v[196:199], v[88:91]
	v_mfma_f32_16x16x32_bf16 v[76:79], v[134:137], v[204:207], v[76:79]
	v_mfma_f32_16x16x32_bf16 v[72:75], v[142:145], v[204:207], v[72:75]
	v_mfma_f32_16x16x32_bf16 v[116:119], v[156:159], v[172:175], v[116:119]
	v_mfma_f32_16x16x32_bf16 v[112:115], v[164:167], v[172:175], v[112:115]
	v_mfma_f32_16x16x32_bf16 v[100:103], v[156:159], v[180:183], v[100:103]
	v_mfma_f32_16x16x32_bf16 v[96:99], v[164:167], v[180:183], v[96:99]
	v_mfma_f32_16x16x32_bf16 v[84:87], v[156:159], v[192:195], v[84:87]
	v_mfma_f32_16x16x32_bf16 v[80:83], v[164:167], v[192:195], v[80:83]
	v_mfma_f32_16x16x32_bf16 v[68:71], v[156:159], v[200:203], v[68:71]
	v_mfma_f32_16x16x32_bf16 v[64:67], v[164:167], v[200:203], v[64:67]
	v_mfma_f32_16x16x32_bf16 v[116:119], v[160:163], v[176:179], v[116:119]
	v_mfma_f32_16x16x32_bf16 v[112:115], v[168:171], v[176:179], v[112:115]
	v_mfma_f32_16x16x32_bf16 v[100:103], v[160:163], v[186:189], v[100:103]
	v_mfma_f32_16x16x32_bf16 v[96:99], v[168:171], v[186:189], v[96:99]
	v_mfma_f32_16x16x32_bf16 v[84:87], v[160:163], v[196:199], v[84:87]
	v_mfma_f32_16x16x32_bf16 v[80:83], v[168:171], v[196:199], v[80:83]
	v_mfma_f32_16x16x32_bf16 v[68:71], v[160:163], v[204:207], v[68:71]
	v_mfma_f32_16x16x32_bf16 v[64:67], v[168:171], v[204:207], v[64:67]
	s_barrier
	s_add_i32 s8, s8, s14
	v_lshl_add_u64 v[208:209], s[46:47], 0, v[128:129]
	s_mov_b32 m0, s8
	ds_read_b128 v[172:175], v191 offset:16384
	ds_read_b128 v[176:179], v191 offset:17408
	ds_read_b128 v[180:183], v191 offset:18432
	ds_read_b128 v[186:189], v191 offset:19456
	ds_read_b128 v[192:195], v191 offset:20480
	ds_read_b128 v[196:199], v191 offset:21504
	ds_read_b128 v[200:203], v191 offset:22528
	ds_read_b128 v[204:207], v191 offset:23552
	global_load_lds_dwordx4 v[208:209], off
	s_add_i32 m0, s8, 0x2000
	s_add_u32 s84, s46, 0xb0000
	v_lshl_add_u64 v[210:211], s[46:47], 0, v[146:147]
	s_addc_u32 s85, s47, 0
	s_add_i32 s8, s88, s14
	global_load_lds_dwordx4 v[210:211], off
	v_lshl_add_u64 v[214:215], s[84:85], 0, v[128:129]
	s_mov_b32 m0, s8
	v_lshl_add_u64 v[222:223], s[64:65], 0, v[148:149]
	global_load_lds_dwordx4 v[214:215], off
	v_lshl_add_u64 v[214:215], s[84:85], 0, v[146:147]
	s_add_i32 m0, s8, 0x2000
	s_nop 0
	global_load_lds_dwordx4 v[214:215], off
	v_lshl_add_u64 v[214:215], s[64:65], 0, v[150:151]
	s_mov_b32 m0, s15
	s_nop 0
	global_load_lds_dwordx4 v[214:215], off
	s_mov_b32 m0, s18
	s_nop 0
	global_load_lds_dwordx4 v[222:223], off
	s_waitcnt vmcnt(8)
	s_waitcnt lgkmcnt(0)
	s_barrier
; #define PG8_STAGE(bufoff, gbase, voff) do { _Pragma("unroll") for (int _i = 0; _i < 2; ++_i) \
;         __builtin_amdgcn_global_load_lds((const unsigned*)((const char*)(gbase) + (voff)[_i]), (PG8_LAS unsigned*)(lds + (bufoff) + ldsw + _i * 8192), 16, 0, 0); } while (0)
; #define PG8_LDA(dst, b, h) do { _Pragma("unroll") for (int m = 0; m < 4; ++m) _Pragma("unroll") for (int k = 0; k < 2; ++k) dst[m][k] = *(const PG8_LAS bf16x8*)(lds + PG8_SA(b, h) + aoff + m * 2048 + k * 1024); } while (0)
; #define PG8_LDB(dst, b, h) do { _Pragma("unroll") for (int n = 0; n < 2; ++n) _Pragma("unroll") for (int k = 0; k < 2; ++k) dst[n][k] = *(const PG8_LAS bf16x8*)(lds + PG8_SB(b, h) + boff + n * 2048 + k * 1024); } while (0)
; #define PG8_MMA(ai, bj, At, Bt) do { __builtin_amdgcn_s_setprio(1); _Pragma("unroll") for (int m = 0; m < 4; ++m) _Pragma("unroll") for (int n = 0; n < 2; ++n) _Pragma("unroll") for (int k = 0; k < 2; ++k) \
;         acc[ai][bj][m][n] = __builtin_amdgcn_mfma_f32_16x16x32_bf16(Bt[n][k], At[m][k], acc[ai][bj][m][n], 0, 0, 0); __builtin_amdgcn_s_setprio(0); } while (0)
; #define PG8_WAIT_V(n) asm volatile("s_waitcnt vmcnt(" #n ")" ::: "memory")
; #define PG8_WAIT_L(n) asm volatile("s_waitcnt lgkmcnt(" #n ")" ::: "memory")
; #define PG8_BAR __builtin_amdgcn_s_barrier()
; #define PG8_SCHED __builtin_amdgcn_sched_barrier(0)
; template <class Epi, class Sched, bool ALIGN_EPI = false, bool SP2 = false>
; __device__ __forceinline__ void gemm_phase(PG8_LAS unsigned char* lds, const Gemm g, const Sched& S, const Epi& E) {
;     ...
;             PG8_WAIT_V(8); PG8_WAIT_L(0); PG8_BAR; PG8_MMA(1, 0, At, B0); PG8_MMA(1, 1, At, B1); PG8_BAR; PG8_SCHED;
;             PG8_LDB(B0, 1, 0); PG8_LDB(B1, 1, 1); PG8_SCHED; PG8_LDA(At, 1, 0); PG8_STAGE(PG8_SA(0, 1), a2 + hstep, voffA);
;             PG8_WAIT_V(8); PG8_WAIT_L(0); PG8_BAR; PG8_MMA(0, 0, At, B0); PG8_MMA(0, 1, At, B1); PG8_BAR; PG8_SCHED;
	s_waitcnt lgkmcnt(0)
	v_mfma_f32_16x16x32_bf16 v[60:63], v[130:133], v[172:175], v[60:63]
	v_mfma_f32_16x16x32_bf16 v[56:59], v[138:141], v[172:175], v[56:59]
	v_mfma_f32_16x16x32_bf16 v[44:47], v[130:133], v[180:183], v[44:47]
	v_mfma_f32_16x16x32_bf16 v[40:43], v[138:141], v[180:183], v[40:43]
	v_mfma_f32_16x16x32_bf16 v[28:31], v[130:133], v[192:195], v[28:31]
	v_mfma_f32_16x16x32_bf16 v[24:27], v[138:141], v[192:195], v[24:27]
	v_mfma_f32_16x16x32_bf16 v[12:15], v[130:133], v[200:203], v[12:15]
	v_mfma_f32_16x16x32_bf16 v[8:11], v[138:141], v[200:203], v[8:11]
	v_mfma_f32_16x16x32_bf16 v[60:63], v[134:137], v[176:179], v[60:63]
	v_mfma_f32_16x16x32_bf16 v[56:59], v[142:145], v[176:179], v[56:59]
	v_mfma_f32_16x16x32_bf16 v[44:47], v[134:137], v[186:189], v[44:47]
	v_mfma_f32_16x16x32_bf16 v[40:43], v[142:145], v[186:189], v[40:43]
	v_mfma_f32_16x16x32_bf16 v[28:31], v[134:137], v[196:199], v[28:31]
	v_mfma_f32_16x16x32_bf16 v[24:27], v[142:145], v[196:199], v[24:27]
	v_mfma_f32_16x16x32_bf16 v[12:15], v[134:137], v[204:207], v[12:15]
	v_mfma_f32_16x16x32_bf16 v[8:11], v[142:145], v[204:207], v[8:11]
	v_mfma_f32_16x16x32_bf16 v[52:55], v[156:159], v[172:175], v[52:55]
	v_mfma_f32_16x16x32_bf16 v[48:51], v[164:167], v[172:175], v[48:51]
	v_mfma_f32_16x16x32_bf16 v[36:39], v[156:159], v[180:183], v[36:39]
	v_mfma_f32_16x16x32_bf16 v[32:35], v[164:167], v[180:183], v[32:35]
	v_mfma_f32_16x16x32_bf16 v[20:23], v[156:159], v[192:195], v[20:23]
	v_mfma_f32_16x16x32_bf16 v[16:19], v[164:167], v[192:195], v[16:19]
	v_mfma_f32_16x16x32_bf16 v[4:7], v[156:159], v[200:203], v[4:7]
	v_mfma_f32_16x16x32_bf16 v[0:3], v[164:167], v[200:203], v[0:3]
	v_mfma_f32_16x16x32_bf16 v[52:55], v[160:163], v[176:179], v[52:55]
	v_mfma_f32_16x16x32_bf16 v[48:51], v[168:171], v[176:179], v[48:51]
	v_mfma_f32_16x16x32_bf16 v[36:39], v[160:163], v[186:189], v[36:39]
	v_mfma_f32_16x16x32_bf16 v[32:35], v[168:171], v[186:189], v[32:35]
	v_mfma_f32_16x16x32_bf16 v[20:23], v[160:163], v[196:199], v[20:23]
	v_mfma_f32_16x16x32_bf16 v[16:19], v[168:171], v[196:199], v[16:19]
	v_mfma_f32_16x16x32_bf16 v[4:7], v[160:163], v[204:207], v[4:7]
	v_mfma_f32_16x16x32_bf16 v[0:3], v[168:171], v[204:207], v[0:3]
	s_barrier
	s_add_i32 s8, 0, 0x18000
	s_add_i32 s84, 0, 0x1c000
	v_add_u32_e32 v142, s8, v185
	v_add_u32_e32 v168, s84, v185
	ds_read_b128 v[130:133], v142
	ds_read_b128 v[134:137], v142 offset:1024
	ds_read_b128 v[138:141], v142 offset:2048
	ds_read_b128 v[142:145], v142 offset:3072
	ds_read_b128 v[156:159], v168
	ds_read_b128 v[160:163], v168 offset:1024
	ds_read_b128 v[164:167], v168 offset:2048
	ds_read_b128 v[168:171], v168 offset:3072
	s_add_u32 s64, s64, 0xb0000
	s_addc_u32 s65, s65, 0
	s_mov_b32 m0, s19
	v_lshl_add_u64 v[228:229], s[64:65], 0, v[150:151]
	ds_read_b128 v[172:175], v191 offset:32768
	ds_read_b128 v[176:179], v191 offset:33792
	ds_read_b128 v[180:183], v191 offset:34816
	ds_read_b128 v[186:189], v191 offset:35840
	ds_read_b128 v[192:195], v191 offset:36864
	ds_read_b128 v[196:199], v191 offset:37888
	ds_read_b128 v[200:203], v191 offset:38912
	ds_read_b128 v[204:207], v191 offset:39936
	global_load_lds_dwordx4 v[228:229], off
	v_lshl_add_u64 v[228:229], s[64:65], 0, v[148:149]
	s_mov_b32 m0, s20
	s_nop 0
	global_load_lds_dwordx4 v[228:229], off
	s_waitcnt vmcnt(8)
	s_waitcnt lgkmcnt(0)
	s_barrier
	s_waitcnt lgkmcnt(0)
	v_mfma_f32_16x16x32_bf16 v[124:127], v[130:133], v[172:175], v[124:127]
	v_mfma_f32_16x16x32_bf16 v[120:123], v[138:141], v[172:175], v[120:123]
	v_mfma_f32_16x16x32_bf16 v[108:111], v[130:133], v[180:183], v[108:111]
	v_mfma_f32_16x16x32_bf16 v[104:107], v[138:141], v[180:183], v[104:107]
	v_mfma_f32_16x16x32_bf16 v[92:95], v[130:133], v[192:195], v[92:95]
	v_mfma_f32_16x16x32_bf16 v[88:91], v[138:141], v[192:195], v[88:91]
	v_mfma_f32_16x16x32_bf16 v[76:79], v[130:133], v[200:203], v[76:79]
	v_mfma_f32_16x16x32_bf16 v[72:75], v[138:141], v[200:203], v[72:75]
	v_mfma_f32_16x16x32_bf16 v[124:127], v[134:137], v[176:179], v[124:127]
	v_mfma_f32_16x16x32_bf16 v[120:123], v[142:145], v[176:179], v[120:123]
	v_mfma_f32_16x16x32_bf16 v[108:111], v[134:137], v[186:189], v[108:111]
	v_mfma_f32_16x16x32_bf16 v[104:107], v[142:145], v[186:189], v[104:107]
	v_mfma_f32_16x16x32_bf16 v[92:95], v[134:137], v[196:199], v[92:95]
	v_mfma_f32_16x16x32_bf16 v[88:91], v[142:145], v[196:199], v[88:91]
	v_mfma_f32_16x16x32_bf16 v[76:79], v[134:137], v[204:207], v[76:79]
	v_mfma_f32_16x16x32_bf16 v[72:75], v[142:145], v[204:207], v[72:75]
	v_mfma_f32_16x16x32_bf16 v[116:119], v[156:159], v[172:175], v[116:119]
	v_mfma_f32_16x16x32_bf16 v[112:115], v[164:167], v[172:175], v[112:115]
	v_mfma_f32_16x16x32_bf16 v[100:103], v[156:159], v[180:183], v[100:103]
	v_mfma_f32_16x16x32_bf16 v[96:99], v[164:167], v[180:183], v[96:99]
	v_mfma_f32_16x16x32_bf16 v[84:87], v[156:159], v[192:195], v[84:87]
	v_mfma_f32_16x16x32_bf16 v[80:83], v[164:167], v[192:195], v[80:83]
	v_mfma_f32_16x16x32_bf16 v[68:71], v[156:159], v[200:203], v[68:71]
	v_mfma_f32_16x16x32_bf16 v[64:67], v[164:167], v[200:203], v[64:67]
	v_mfma_f32_16x16x32_bf16 v[116:119], v[160:163], v[176:179], v[116:119]
	v_mfma_f32_16x16x32_bf16 v[112:115], v[168:171], v[176:179], v[112:115]
	v_mfma_f32_16x16x32_bf16 v[100:103], v[160:163], v[186:189], v[100:103]
	v_mfma_f32_16x16x32_bf16 v[96:99], v[168:171], v[186:189], v[96:99]
	v_mfma_f32_16x16x32_bf16 v[84:87], v[160:163], v[196:199], v[84:87]
	v_mfma_f32_16x16x32_bf16 v[80:83], v[168:171], v[196:199], v[80:83]
	v_mfma_f32_16x16x32_bf16 v[68:71], v[160:163], v[204:207], v[68:71]
	v_mfma_f32_16x16x32_bf16 v[64:67], v[168:171], v[204:207], v[64:67]
	s_barrier
; #define PG8_STAGE(bufoff, gbase, voff) do { _Pragma("unroll") for (int _i = 0; _i < 2; ++_i) \
;         __builtin_amdgcn_global_load_lds((const unsigned*)((const char*)(gbase) + (voff)[_i]), (PG8_LAS unsigned*)(lds + (bufoff) + ldsw + _i * 8192), 16, 0, 0); } while (0)
; #define PG8_LDA(dst, b, h) do { _Pragma("unroll") for (int m = 0; m < 4; ++m) _Pragma("unroll") for (int k = 0; k < 2; ++k) dst[m][k] = *(const PG8_LAS bf16x8*)(lds + PG8_SA(b, h) + aoff + m * 2048 + k * 1024); } while (0)
; #define PG8_MMA(ai, bj, At, Bt) do { __builtin_amdgcn_s_setprio(1); _Pragma("unroll") for (int m = 0; m < 4; ++m) _Pragma("unroll") for (int n = 0; n < 2; ++n) _Pragma("unroll") for (int k = 0; k < 2; ++k) \
;         acc[ai][bj][m][n] = __builtin_amdgcn_mfma_f32_16x16x32_bf16(Bt[n][k], At[m][k], acc[ai][bj][m][n], 0, 0, 0); __builtin_amdgcn_s_setprio(0); } while (0)
; #define PG8_WAIT_V(n) asm volatile("s_waitcnt vmcnt(" #n ")" ::: "memory")
; #define PG8_WAIT_L(n) asm volatile("s_waitcnt lgkmcnt(" #n ")" ::: "memory")
; #define PG8_BAR __builtin_amdgcn_s_barrier()
; #define PG8_SCHED __builtin_amdgcn_sched_barrier(0)
; template <class Epi, class Sched, bool ALIGN_EPI = false, bool SP2 = false>
; __device__ __forceinline__ void gemm_phase(PG8_LAS unsigned char* lds, const Gemm g, const Sched& S, const Epi& E) {
;     ...
;             PG8_LDA(At, 1, 1); PG8_STAGE(PG8_SB(1, 0), b3, voffB); PG8_STAGE(PG8_SB(1, 1), b3 + hstep, voffB); PG8_STAGE(PG8_SA(1, 0), a3, voffA);
;             PG8_WAIT_V(8); PG8_WAIT_L(0); PG8_BAR; PG8_MMA(1, 0, At, B0); PG8_MMA(1, 1, At, B1); PG8_BAR; PG8_SCHED;
	s_add_i32 s8, s8, s14
	v_lshl_add_u64 v[208:209], v[208:209], 0, s[90:91]
	s_mov_b32 m0, s8
	ds_read_b128 v[172:175], v191 offset:49152
	ds_read_b128 v[176:179], v191 offset:50176
	ds_read_b128 v[180:183], v191 offset:51200
	ds_read_b128 v[186:189], v191 offset:52224
	ds_read_b128 v[192:195], v191 offset:53248
	ds_read_b128 v[196:199], v191 offset:54272
	ds_read_b128 v[200:203], v191 offset:55296
	ds_read_b128 v[204:207], v191 offset:56320
	global_load_lds_dwordx4 v[208:209], off
	s_add_i32 m0, s8, 0x2000
	s_add_u32 s46, s46, 0xb0080
	v_lshl_add_u64 v[208:209], v[210:211], 0, s[90:91]
	s_addc_u32 s47, s47, 0
	s_add_i32 s8, s84, s14
	global_load_lds_dwordx4 v[208:209], off
	v_lshl_add_u64 v[208:209], s[46:47], 0, v[128:129]
	s_mov_b32 m0, s8
	s_nop 0
	global_load_lds_dwordx4 v[208:209], off
	v_lshl_add_u64 v[208:209], s[46:47], 0, v[146:147]
	s_add_i32 m0, s8, 0x2000
	s_nop 0
	global_load_lds_dwordx4 v[208:209], off
	v_lshl_add_u64 v[208:209], v[214:215], 0, s[90:91]
	s_mov_b32 m0, s27
	s_nop 0
	global_load_lds_dwordx4 v[208:209], off
	v_lshl_add_u64 v[208:209], v[222:223], 0, s[90:91]
	s_mov_b32 m0, s28
	s_nop 0
	global_load_lds_dwordx4 v[208:209], off
	s_waitcnt vmcnt(8)
	s_waitcnt lgkmcnt(0)
	s_barrier
	s_waitcnt lgkmcnt(0)
	v_mfma_f32_16x16x32_bf16 v[60:63], v[130:133], v[172:175], v[60:63]
	v_mfma_f32_16x16x32_bf16 v[56:59], v[138:141], v[172:175], v[56:59]
	v_mfma_f32_16x16x32_bf16 v[44:47], v[130:133], v[180:183], v[44:47]
	v_mfma_f32_16x16x32_bf16 v[40:43], v[138:141], v[180:183], v[40:43]
	v_mfma_f32_16x16x32_bf16 v[28:31], v[130:133], v[192:195], v[28:31]
	v_mfma_f32_16x16x32_bf16 v[24:27], v[138:141], v[192:195], v[24:27]
	v_mfma_f32_16x16x32_bf16 v[12:15], v[130:133], v[200:203], v[12:15]
	v_mfma_f32_16x16x32_bf16 v[8:11], v[138:141], v[200:203], v[8:11]
	v_mfma_f32_16x16x32_bf16 v[60:63], v[134:137], v[176:179], v[60:63]
	v_mfma_f32_16x16x32_bf16 v[56:59], v[142:145], v[176:179], v[56:59]
	v_mfma_f32_16x16x32_bf16 v[44:47], v[134:137], v[186:189], v[44:47]
	v_mfma_f32_16x16x32_bf16 v[40:43], v[142:145], v[186:189], v[40:43]
	v_mfma_f32_16x16x32_bf16 v[28:31], v[134:137], v[196:199], v[28:31]
	v_mfma_f32_16x16x32_bf16 v[24:27], v[142:145], v[196:199], v[24:27]
	v_mfma_f32_16x16x32_bf16 v[12:15], v[134:137], v[204:207], v[12:15]
	v_mfma_f32_16x16x32_bf16 v[8:11], v[142:145], v[204:207], v[8:11]
	v_mfma_f32_16x16x32_bf16 v[52:55], v[156:159], v[172:175], v[52:55]
	v_mfma_f32_16x16x32_bf16 v[48:51], v[164:167], v[172:175], v[48:51]
	v_mfma_f32_16x16x32_bf16 v[36:39], v[156:159], v[180:183], v[36:39]
	v_mfma_f32_16x16x32_bf16 v[32:35], v[164:167], v[180:183], v[32:35]
	v_mfma_f32_16x16x32_bf16 v[20:23], v[156:159], v[192:195], v[20:23]
	v_mfma_f32_16x16x32_bf16 v[16:19], v[164:167], v[192:195], v[16:19]
	v_mfma_f32_16x16x32_bf16 v[4:7], v[156:159], v[200:203], v[4:7]
	v_mfma_f32_16x16x32_bf16 v[0:3], v[164:167], v[200:203], v[0:3]
	v_mfma_f32_16x16x32_bf16 v[52:55], v[160:163], v[176:179], v[52:55]
	v_mfma_f32_16x16x32_bf16 v[48:51], v[168:171], v[176:179], v[48:51]
	v_mfma_f32_16x16x32_bf16 v[36:39], v[160:163], v[186:189], v[36:39]
	v_mfma_f32_16x16x32_bf16 v[32:35], v[168:171], v[186:189], v[32:35]
	v_mfma_f32_16x16x32_bf16 v[20:23], v[160:163], v[196:199], v[20:23]
	v_mfma_f32_16x16x32_bf16 v[16:19], v[168:171], v[196:199], v[16:19]
	v_mfma_f32_16x16x32_bf16 v[4:7], v[160:163], v[204:207], v[4:7]
	v_mfma_f32_16x16x32_bf16 v[0:3], v[168:171], v[204:207], v[0:3]
	s_barrier
	s_add_i32 s70, s70, 2
	s_add_u32 s36, s36, 0x100
	s_addc_u32 s37, s37, 0
	s_cmp_gt_u32 s70, 41
	s_mov_b64 s[96:97], s[44:45]
	s_cbranch_scc0 .LBB0_957
	s_and_b64 vcc, exec, s[58:59]
	s_cbranch_vccz .LBB0_960
	s_barrier

; #define PG8_STAGE(bufoff, gbase, voff) do { _Pragma("unroll") for (int _i = 0; _i < 2; ++_i) \
;         __builtin_amdgcn_global_load_lds((const unsigned*)((const char*)(gbase) + (voff)[_i]), (PG8_LAS unsigned*)(lds + (bufoff) + ldsw + _i * 8192), 16, 0, 0); } while (0)
; #define PG8_LDA(dst, b, h) do { _Pragma("unroll") for (int m = 0; m < 4; ++m) _Pragma("unroll") for (int k = 0; k < 2; ++k) dst[m][k] = *(const PG8_LAS bf16x8*)(lds + PG8_SA(b, h) + aoff + m * 2048 + k * 1024); } while (0)
; #define PG8_LDB(dst, b, h) do { _Pragma("unroll") for (int n = 0; n < 2; ++n) _Pragma("unroll") for (int k = 0; k < 2; ++k) dst[n][k] = *(const PG8_LAS bf16x8*)(lds + PG8_SB(b, h) + boff + n * 2048 + k * 1024); } while (0)
; #define PG8_MMA(ai, bj, At, Bt) do { __builtin_amdgcn_s_setprio(1); _Pragma("unroll") for (int m = 0; m < 4; ++m) _Pragma("unroll") for (int n = 0; n < 2; ++n) _Pragma("unroll") for (int k = 0; k < 2; ++k) \
;         acc[ai][bj][m][n] = __builtin_amdgcn_mfma_f32_16x16x32_bf16(Bt[n][k], At[m][k], acc[ai][bj][m][n], 0, 0, 0); __builtin_amdgcn_s_setprio(0); } while (0)
; #define PG8_WAIT_V(n) asm volatile("s_waitcnt vmcnt(" #n ")" ::: "memory")
; #define PG8_BAR __builtin_amdgcn_s_barrier()
; template <class Epi, class Sched, bool ALIGN_EPI = false, bool SP2 = false>
; __device__ __forceinline__ void gemm_phase(PG8_LAS unsigned char* lds, const Gemm g, const Sched& S, const Epi& E) {
;     ...
;         for (int t = 0; t < nt; t += 2) {
;             const bool last = (t == nt - 2);
;             const char* a1 = cA + (size_t)(t + 1) * kstep;
;             const char* a2 = last ? nA : cA + (size_t)(t + 2) * kstep; const char* b2 = last ? nB : cB + (size_t)(t + 2) * kstep;
;             const char* a3 = a2 + kstep; const char* b3 = b2 + kstep;
;             if (last && has_next) S.a_ready(nxt);
;             if constexpr (SP2) {
;             PG8_LDB(B0, 0, 0); PG8_LDB(B1, 0, 1); PG8_SCHED; PG8_LDA(At, 0, 0); PG8_STAGE(PG8_SA(1, 1), a1 + hstep, voffA);
;             PG8_WAIT_V(8); PG8_WAIT_L(0); PG8_BAR; PG8_MMA(0, 0, At, B0); PG8_MMA(0, 1, At, B1); PG8_BAR; PG8_SCHED;
;             PG8_LDA(At, 0, 1); PG8_STAGE(PG8_SB(0, 0), b2, voffB); PG8_STAGE(PG8_SB(0, 1), b2 + hstep, voffB); PG8_STAGE(PG8_SA(0, 0), a2, voffA);
;             PG8_WAIT_V(8); PG8_WAIT_L(0); PG8_BAR; PG8_MMA(1, 0, At, B0); PG8_MMA(1, 1, At, B1); PG8_BAR; PG8_SCHED;
.LBB0_995:
	s_add_u32 s42, s96, 0x100
	s_addc_u32 s43, s97, 0
	s_add_i32 s8, 0, 0x10000
	s_cmp_eq_u32 s84, 40
	s_cselect_b32 s65, s67, s43
	s_cselect_b32 s64, s66, s42
	s_cselect_b32 s47, s73, s37
	s_cselect_b32 s46, s72, s36
	s_add_i32 s85, 0, 0x14000
	v_add_u32_e32 v142, s8, v201
	v_add_u32_e32 v168, s85, v201
	ds_read_b128 v[130:133], v142
	ds_read_b128 v[134:137], v142 offset:1024
	ds_read_b128 v[138:141], v142 offset:2048
	ds_read_b128 v[142:145], v142 offset:3072
	ds_read_b128 v[156:159], v168
	ds_read_b128 v[160:163], v168 offset:1024
	ds_read_b128 v[164:167], v168 offset:2048
	ds_read_b128 v[168:171], v168 offset:3072
	v_lshl_add_u64 v[208:209], s[96:97], 0, v[152:153]
	s_add_i32 m0, s15, 0xc000
	ds_read_b128 v[172:175], v203
	ds_read_b128 v[176:179], v203 offset:1024
	ds_read_b128 v[180:183], v203 offset:2048
	ds_read_b128 v[184:187], v203 offset:3072
	ds_read_b128 v[188:191], v203 offset:4096
	ds_read_b128 v[192:195], v203 offset:5120
	ds_read_b128 v[196:199], v203 offset:6144
	ds_read_b128 v[204:207], v203 offset:7168
	global_load_lds_dwordx4 v[208:209], off
	v_lshl_add_u64 v[208:209], s[96:97], 0, v[154:155]
	s_add_i32 m0, s15, 0xe000
	s_nop 0
	global_load_lds_dwordx4 v[208:209], off
	s_waitcnt vmcnt(8)
	s_waitcnt lgkmcnt(0)
	s_barrier
	s_waitcnt lgkmcnt(0)
	v_mfma_f32_16x16x32_bf16 v[124:127], v[130:133], v[172:175], v[124:127]
	v_mfma_f32_16x16x32_bf16 v[120:123], v[138:141], v[172:175], v[120:123]
	v_mfma_f32_16x16x32_bf16 v[108:111], v[130:133], v[180:183], v[108:111]
	v_mfma_f32_16x16x32_bf16 v[104:107], v[138:141], v[180:183], v[104:107]
	v_mfma_f32_16x16x32_bf16 v[92:95], v[130:133], v[188:191], v[92:95]
	v_mfma_f32_16x16x32_bf16 v[88:91], v[138:141], v[188:191], v[88:91]
	v_mfma_f32_16x16x32_bf16 v[76:79], v[130:133], v[196:199], v[76:79]
	v_mfma_f32_16x16x32_bf16 v[72:75], v[138:141], v[196:199], v[72:75]
	v_mfma_f32_16x16x32_bf16 v[124:127], v[134:137], v[176:179], v[124:127]
	v_mfma_f32_16x16x32_bf16 v[120:123], v[142:145], v[176:179], v[120:123]
	v_mfma_f32_16x16x32_bf16 v[108:111], v[134:137], v[184:187], v[108:111]
	v_mfma_f32_16x16x32_bf16 v[104:107], v[142:145], v[184:187], v[104:107]
	v_mfma_f32_16x16x32_bf16 v[92:95], v[134:137], v[192:195], v[92:95]
	v_mfma_f32_16x16x32_bf16 v[88:91], v[142:145], v[192:195], v[88:91]
	v_mfma_f32_16x16x32_bf16 v[76:79], v[134:137], v[204:207], v[76:79]
	v_mfma_f32_16x16x32_bf16 v[72:75], v[142:145], v[204:207], v[72:75]
	v_mfma_f32_16x16x32_bf16 v[116:119], v[156:159], v[172:175], v[116:119]
	v_mfma_f32_16x16x32_bf16 v[112:115], v[164:167], v[172:175], v[112:115]
	v_mfma_f32_16x16x32_bf16 v[100:103], v[156:159], v[180:183], v[100:103]
	v_mfma_f32_16x16x32_bf16 v[96:99], v[164:167], v[180:183], v[96:99]
	v_mfma_f32_16x16x32_bf16 v[84:87], v[156:159], v[188:191], v[84:87]
	v_mfma_f32_16x16x32_bf16 v[80:83], v[164:167], v[188:191], v[80:83]
	v_mfma_f32_16x16x32_bf16 v[68:71], v[156:159], v[196:199], v[68:71]
	v_mfma_f32_16x16x32_bf16 v[64:67], v[164:167], v[196:199], v[64:67]
	v_mfma_f32_16x16x32_bf16 v[116:119], v[160:163], v[176:179], v[116:119]
	v_mfma_f32_16x16x32_bf16 v[112:115], v[168:171], v[176:179], v[112:115]
	v_mfma_f32_16x16x32_bf16 v[100:103], v[160:163], v[184:187], v[100:103]
	v_mfma_f32_16x16x32_bf16 v[96:99], v[168:171], v[184:187], v[96:99]
	v_mfma_f32_16x16x32_bf16 v[84:87], v[160:163], v[192:195], v[84:87]
	v_mfma_f32_16x16x32_bf16 v[80:83], v[168:171], v[192:195], v[80:83]
	v_mfma_f32_16x16x32_bf16 v[68:71], v[160:163], v[204:207], v[68:71]
	v_mfma_f32_16x16x32_bf16 v[64:67], v[168:171], v[204:207], v[64:67]
	s_barrier
	s_add_i32 s8, s8, s14
	v_lshl_add_u64 v[208:209], s[46:47], 0, v[128:129]
	s_mov_b32 m0, s8
	ds_read_b128 v[172:175], v203 offset:16384
	ds_read_b128 v[176:179], v203 offset:17408
	ds_read_b128 v[180:183], v203 offset:18432
	ds_read_b128 v[184:187], v203 offset:19456
	ds_read_b128 v[188:191], v203 offset:20480
	ds_read_b128 v[192:195], v203 offset:21504
	ds_read_b128 v[196:199], v203 offset:22528
	ds_read_b128 v[204:207], v203 offset:23552
	global_load_lds_dwordx4 v[208:209], off
	s_add_i32 m0, s8, 0x2000
	s_add_u32 s96, s46, 0xb0000
	v_lshl_add_u64 v[210:211], s[46:47], 0, v[146:147]
	s_addc_u32 s97, s47, 0
	s_add_i32 s8, s85, s14
	global_load_lds_dwordx4 v[210:211], off
	v_lshl_add_u64 v[214:215], s[96:97], 0, v[128:129]
	s_mov_b32 m0, s8
	v_lshl_add_u64 v[222:223], s[64:65], 0, v[148:149]
	global_load_lds_dwordx4 v[214:215], off
	v_lshl_add_u64 v[214:215], s[96:97], 0, v[146:147]
	s_add_i32 m0, s8, 0x2000
	s_nop 0
	global_load_lds_dwordx4 v[214:215], off
	v_lshl_add_u64 v[214:215], s[64:65], 0, v[150:151]
	s_mov_b32 m0, s15
	s_nop 0
	global_load_lds_dwordx4 v[214:215], off
	s_mov_b32 m0, s18
	s_nop 0
	global_load_lds_dwordx4 v[222:223], off
	s_waitcnt vmcnt(8)
	s_waitcnt lgkmcnt(0)
	s_barrier
; #define PG8_STAGE(bufoff, gbase, voff) do { _Pragma("unroll") for (int _i = 0; _i < 2; ++_i) \
;         __builtin_amdgcn_global_load_lds((const unsigned*)((const char*)(gbase) + (voff)[_i]), (PG8_LAS unsigned*)(lds + (bufoff) + ldsw + _i * 8192), 16, 0, 0); } while (0)
; #define PG8_LDA(dst, b, h) do { _Pragma("unroll") for (int m = 0; m < 4; ++m) _Pragma("unroll") for (int k = 0; k < 2; ++k) dst[m][k] = *(const PG8_LAS bf16x8*)(lds + PG8_SA(b, h) + aoff + m * 2048 + k * 1024); } while (0)
; #define PG8_LDB(dst, b, h) do { _Pragma("unroll") for (int n = 0; n < 2; ++n) _Pragma("unroll") for (int k = 0; k < 2; ++k) dst[n][k] = *(const PG8_LAS bf16x8*)(lds + PG8_SB(b, h) + boff + n * 2048 + k * 1024); } while (0)
; #define PG8_MMA(ai, bj, At, Bt) do { __builtin_amdgcn_s_setprio(1); _Pragma("unroll") for (int m = 0; m < 4; ++m) _Pragma("unroll") for (int n = 0; n < 2; ++n) _Pragma("unroll") for (int k = 0; k < 2; ++k) \
;         acc[ai][bj][m][n] = __builtin_amdgcn_mfma_f32_16x16x32_bf16(Bt[n][k], At[m][k], acc[ai][bj][m][n], 0, 0, 0); __builtin_amdgcn_s_setprio(0); } while (0)
; #define PG8_WAIT_V(n) asm volatile("s_waitcnt vmcnt(" #n ")" ::: "memory")
; #define PG8_WAIT_L(n) asm volatile("s_waitcnt lgkmcnt(" #n ")" ::: "memory")
; #define PG8_BAR __builtin_amdgcn_s_barrier()
; #define PG8_SCHED __builtin_amdgcn_sched_barrier(0)
; template <class Epi, class Sched, bool ALIGN_EPI = false, bool SP2 = false>
; __device__ __forceinline__ void gemm_phase(PG8_LAS unsigned char* lds, const Gemm g, const Sched& S, const Epi& E) {
;     ...
;             PG8_WAIT_V(8); PG8_WAIT_L(0); PG8_BAR; PG8_MMA(1, 0, At, B0); PG8_MMA(1, 1, At, B1); PG8_BAR; PG8_SCHED;
;             PG8_LDB(B0, 1, 0); PG8_LDB(B1, 1, 1); PG8_SCHED; PG8_LDA(At, 1, 0); PG8_STAGE(PG8_SA(0, 1), a2 + hstep, voffA);
;             PG8_WAIT_V(8); PG8_WAIT_L(0); PG8_BAR; PG8_MMA(0, 0, At, B0); PG8_MMA(0, 1, At, B1); PG8_BAR; PG8_SCHED;
	s_waitcnt lgkmcnt(0)
	v_mfma_f32_16x16x32_bf16 v[60:63], v[130:133], v[172:175], v[60:63]
	v_mfma_f32_16x16x32_bf16 v[56:59], v[138:141], v[172:175], v[56:59]
	v_mfma_f32_16x16x32_bf16 v[44:47], v[130:133], v[180:183], v[44:47]
	v_mfma_f32_16x16x32_bf16 v[40:43], v[138:141], v[180:183], v[40:43]
	v_mfma_f32_16x16x32_bf16 v[28:31], v[130:133], v[188:191], v[28:31]
	v_mfma_f32_16x16x32_bf16 v[24:27], v[138:141], v[188:191], v[24:27]
	v_mfma_f32_16x16x32_bf16 v[12:15], v[130:133], v[196:199], v[12:15]
	v_mfma_f32_16x16x32_bf16 v[8:11], v[138:141], v[196:199], v[8:11]
	v_mfma_f32_16x16x32_bf16 v[60:63], v[134:137], v[176:179], v[60:63]
	v_mfma_f32_16x16x32_bf16 v[56:59], v[142:145], v[176:179], v[56:59]
	v_mfma_f32_16x16x32_bf16 v[44:47], v[134:137], v[184:187], v[44:47]
	v_mfma_f32_16x16x32_bf16 v[40:43], v[142:145], v[184:187], v[40:43]
	v_mfma_f32_16x16x32_bf16 v[28:31], v[134:137], v[192:195], v[28:31]
	v_mfma_f32_16x16x32_bf16 v[24:27], v[142:145], v[192:195], v[24:27]
	v_mfma_f32_16x16x32_bf16 v[12:15], v[134:137], v[204:207], v[12:15]
	v_mfma_f32_16x16x32_bf16 v[8:11], v[142:145], v[204:207], v[8:11]
	v_mfma_f32_16x16x32_bf16 v[52:55], v[156:159], v[172:175], v[52:55]
	v_mfma_f32_16x16x32_bf16 v[48:51], v[164:167], v[172:175], v[48:51]
	v_mfma_f32_16x16x32_bf16 v[36:39], v[156:159], v[180:183], v[36:39]
	v_mfma_f32_16x16x32_bf16 v[32:35], v[164:167], v[180:183], v[32:35]
	v_mfma_f32_16x16x32_bf16 v[20:23], v[156:159], v[188:191], v[20:23]
	v_mfma_f32_16x16x32_bf16 v[16:19], v[164:167], v[188:191], v[16:19]
	v_mfma_f32_16x16x32_bf16 v[4:7], v[156:159], v[196:199], v[4:7]
	v_mfma_f32_16x16x32_bf16 v[0:3], v[164:167], v[196:199], v[0:3]
	v_mfma_f32_16x16x32_bf16 v[52:55], v[160:163], v[176:179], v[52:55]
	v_mfma_f32_16x16x32_bf16 v[48:51], v[168:171], v[176:179], v[48:51]
	v_mfma_f32_16x16x32_bf16 v[36:39], v[160:163], v[184:187], v[36:39]
	v_mfma_f32_16x16x32_bf16 v[32:35], v[168:171], v[184:187], v[32:35]
	v_mfma_f32_16x16x32_bf16 v[20:23], v[160:163], v[192:195], v[20:23]
	v_mfma_f32_16x16x32_bf16 v[16:19], v[168:171], v[192:195], v[16:19]
	v_mfma_f32_16x16x32_bf16 v[4:7], v[160:163], v[204:207], v[4:7]
	v_mfma_f32_16x16x32_bf16 v[0:3], v[168:171], v[204:207], v[0:3]
	s_barrier
	s_add_i32 s8, 0, 0x18000
	s_add_i32 s85, 0, 0x1c000
	v_add_u32_e32 v142, s8, v201
	v_add_u32_e32 v168, s85, v201
	ds_read_b128 v[130:133], v142
	ds_read_b128 v[134:137], v142 offset:1024
	ds_read_b128 v[138:141], v142 offset:2048
	ds_read_b128 v[142:145], v142 offset:3072
	ds_read_b128 v[156:159], v168
	ds_read_b128 v[160:163], v168 offset:1024
	ds_read_b128 v[164:167], v168 offset:2048
	ds_read_b128 v[168:171], v168 offset:3072
	s_add_u32 s64, s64, 0xb0000
	s_addc_u32 s65, s65, 0
	s_mov_b32 m0, s19
	v_lshl_add_u64 v[228:229], s[64:65], 0, v[150:151]
	ds_read_b128 v[172:175], v203 offset:32768
	ds_read_b128 v[176:179], v203 offset:33792
	ds_read_b128 v[180:183], v203 offset:34816
	ds_read_b128 v[184:187], v203 offset:35840
	ds_read_b128 v[188:191], v203 offset:36864
	ds_read_b128 v[192:195], v203 offset:37888
	ds_read_b128 v[196:199], v203 offset:38912
	ds_read_b128 v[204:207], v203 offset:39936
	global_load_lds_dwordx4 v[228:229], off
	v_lshl_add_u64 v[228:229], s[64:65], 0, v[148:149]
	s_mov_b32 m0, s20
	s_nop 0
	global_load_lds_dwordx4 v[228:229], off
	s_waitcnt vmcnt(8)
	s_waitcnt lgkmcnt(0)
	s_barrier
	s_waitcnt lgkmcnt(0)
	v_mfma_f32_16x16x32_bf16 v[124:127], v[130:133], v[172:175], v[124:127]
	v_mfma_f32_16x16x32_bf16 v[120:123], v[138:141], v[172:175], v[120:123]
	v_mfma_f32_16x16x32_bf16 v[108:111], v[130:133], v[180:183], v[108:111]
	v_mfma_f32_16x16x32_bf16 v[104:107], v[138:141], v[180:183], v[104:107]
	v_mfma_f32_16x16x32_bf16 v[92:95], v[130:133], v[188:191], v[92:95]
	v_mfma_f32_16x16x32_bf16 v[88:91], v[138:141], v[188:191], v[88:91]
	v_mfma_f32_16x16x32_bf16 v[76:79], v[130:133], v[196:199], v[76:79]
	v_mfma_f32_16x16x32_bf16 v[72:75], v[138:141], v[196:199], v[72:75]
	v_mfma_f32_16x16x32_bf16 v[124:127], v[134:137], v[176:179], v[124:127]
	v_mfma_f32_16x16x32_bf16 v[120:123], v[142:145], v[176:179], v[120:123]
	v_mfma_f32_16x16x32_bf16 v[108:111], v[134:137], v[184:187], v[108:111]
	v_mfma_f32_16x16x32_bf16 v[104:107], v[142:145], v[184:187], v[104:107]
	v_mfma_f32_16x16x32_bf16 v[92:95], v[134:137], v[192:195], v[92:95]
	v_mfma_f32_16x16x32_bf16 v[88:91], v[142:145], v[192:195], v[88:91]
	v_mfma_f32_16x16x32_bf16 v[76:79], v[134:137], v[204:207], v[76:79]
	v_mfma_f32_16x16x32_bf16 v[72:75], v[142:145], v[204:207], v[72:75]
	v_mfma_f32_16x16x32_bf16 v[116:119], v[156:159], v[172:175], v[116:119]
	v_mfma_f32_16x16x32_bf16 v[112:115], v[164:167], v[172:175], v[112:115]
	v_mfma_f32_16x16x32_bf16 v[100:103], v[156:159], v[180:183], v[100:103]
	v_mfma_f32_16x16x32_bf16 v[96:99], v[164:167], v[180:183], v[96:99]
	v_mfma_f32_16x16x32_bf16 v[84:87], v[156:159], v[188:191], v[84:87]
	v_mfma_f32_16x16x32_bf16 v[80:83], v[164:167], v[188:191], v[80:83]
	v_mfma_f32_16x16x32_bf16 v[68:71], v[156:159], v[196:199], v[68:71]
	v_mfma_f32_16x16x32_bf16 v[64:67], v[164:167], v[196:199], v[64:67]
	v_mfma_f32_16x16x32_bf16 v[116:119], v[160:163], v[176:179], v[116:119]
	v_mfma_f32_16x16x32_bf16 v[112:115], v[168:171], v[176:179], v[112:115]
	v_mfma_f32_16x16x32_bf16 v[100:103], v[160:163], v[184:187], v[100:103]
	v_mfma_f32_16x16x32_bf16 v[96:99], v[168:171], v[184:187], v[96:99]
	v_mfma_f32_16x16x32_bf16 v[84:87], v[160:163], v[192:195], v[84:87]
	v_mfma_f32_16x16x32_bf16 v[80:83], v[168:171], v[192:195], v[80:83]
	v_mfma_f32_16x16x32_bf16 v[68:71], v[160:163], v[204:207], v[68:71]
	v_mfma_f32_16x16x32_bf16 v[64:67], v[168:171], v[204:207], v[64:67]
	s_barrier
; #define PG8_STAGE(bufoff, gbase, voff) do { _Pragma("unroll") for (int _i = 0; _i < 2; ++_i) \
;         __builtin_amdgcn_global_load_lds((const unsigned*)((const char*)(gbase) + (voff)[_i]), (PG8_LAS unsigned*)(lds + (bufoff) + ldsw + _i * 8192), 16, 0, 0); } while (0)
; #define PG8_LDA(dst, b, h) do { _Pragma("unroll") for (int m = 0; m < 4; ++m) _Pragma("unroll") for (int k = 0; k < 2; ++k) dst[m][k] = *(const PG8_LAS bf16x8*)(lds + PG8_SA(b, h) + aoff + m * 2048 + k * 1024); } while (0)
; #define PG8_MMA(ai, bj, At, Bt) do { __builtin_amdgcn_s_setprio(1); _Pragma("unroll") for (int m = 0; m < 4; ++m) _Pragma("unroll") for (int n = 0; n < 2; ++n) _Pragma("unroll") for (int k = 0; k < 2; ++k) \
;         acc[ai][bj][m][n] = __builtin_amdgcn_mfma_f32_16x16x32_bf16(Bt[n][k], At[m][k], acc[ai][bj][m][n], 0, 0, 0); __builtin_amdgcn_s_setprio(0); } while (0)
; #define PG8_WAIT_V(n) asm volatile("s_waitcnt vmcnt(" #n ")" ::: "memory")
; #define PG8_WAIT_L(n) asm volatile("s_waitcnt lgkmcnt(" #n ")" ::: "memory")
; #define PG8_BAR __builtin_amdgcn_s_barrier()
; #define PG8_SCHED __builtin_amdgcn_sched_barrier(0)
; template <class Epi, class Sched, bool ALIGN_EPI = false, bool SP2 = false>
; __device__ __forceinline__ void gemm_phase(PG8_LAS unsigned char* lds, const Gemm g, const Sched& S, const Epi& E) {
;     ...
;             PG8_LDA(At, 1, 1); PG8_STAGE(PG8_SB(1, 0), b3, voffB); PG8_STAGE(PG8_SB(1, 1), b3 + hstep, voffB); PG8_STAGE(PG8_SA(1, 0), a3, voffA);
;             PG8_WAIT_V(8); PG8_WAIT_L(0); PG8_BAR; PG8_MMA(1, 0, At, B0); PG8_MMA(1, 1, At, B1); PG8_BAR; PG8_SCHED;
	s_add_i32 s8, s8, s14
	v_lshl_add_u64 v[208:209], v[208:209], 0, s[90:91]
	s_mov_b32 m0, s8
	ds_read_b128 v[172:175], v203 offset:49152
	ds_read_b128 v[176:179], v203 offset:50176
	ds_read_b128 v[180:183], v203 offset:51200
	ds_read_b128 v[184:187], v203 offset:52224
	ds_read_b128 v[188:191], v203 offset:53248
	ds_read_b128 v[192:195], v203 offset:54272
	ds_read_b128 v[196:199], v203 offset:55296
	ds_read_b128 v[204:207], v203 offset:56320
	global_load_lds_dwordx4 v[208:209], off
	s_add_i32 m0, s8, 0x2000
	s_add_u32 s46, s46, 0xb0080
	v_lshl_add_u64 v[208:209], v[210:211], 0, s[90:91]
	s_addc_u32 s47, s47, 0
	s_add_i32 s8, s85, s14
	global_load_lds_dwordx4 v[208:209], off
	v_lshl_add_u64 v[208:209], s[46:47], 0, v[128:129]
	s_mov_b32 m0, s8
	s_nop 0
	global_load_lds_dwordx4 v[208:209], off
	v_lshl_add_u64 v[208:209], s[46:47], 0, v[146:147]
	s_add_i32 m0, s8, 0x2000
	s_nop 0
	global_load_lds_dwordx4 v[208:209], off
	v_lshl_add_u64 v[208:209], v[214:215], 0, s[90:91]
	s_mov_b32 m0, s29
	s_nop 0
	global_load_lds_dwordx4 v[208:209], off
	v_lshl_add_u64 v[208:209], v[222:223], 0, s[90:91]
	s_mov_b32 m0, s30
	s_nop 0
	global_load_lds_dwordx4 v[208:209], off
	s_waitcnt vmcnt(8)
	s_waitcnt lgkmcnt(0)
	s_barrier
	s_waitcnt lgkmcnt(0)
	v_mfma_f32_16x16x32_bf16 v[60:63], v[130:133], v[172:175], v[60:63]
	v_mfma_f32_16x16x32_bf16 v[56:59], v[138:141], v[172:175], v[56:59]
	v_mfma_f32_16x16x32_bf16 v[44:47], v[130:133], v[180:183], v[44:47]
	v_mfma_f32_16x16x32_bf16 v[40:43], v[138:141], v[180:183], v[40:43]
	v_mfma_f32_16x16x32_bf16 v[28:31], v[130:133], v[188:191], v[28:31]
	v_mfma_f32_16x16x32_bf16 v[24:27], v[138:141], v[188:191], v[24:27]
	v_mfma_f32_16x16x32_bf16 v[12:15], v[130:133], v[196:199], v[12:15]
	v_mfma_f32_16x16x32_bf16 v[8:11], v[138:141], v[196:199], v[8:11]
	v_mfma_f32_16x16x32_bf16 v[60:63], v[134:137], v[176:179], v[60:63]
	v_mfma_f32_16x16x32_bf16 v[56:59], v[142:145], v[176:179], v[56:59]
	v_mfma_f32_16x16x32_bf16 v[44:47], v[134:137], v[184:187], v[44:47]
	v_mfma_f32_16x16x32_bf16 v[40:43], v[142:145], v[184:187], v[40:43]
	v_mfma_f32_16x16x32_bf16 v[28:31], v[134:137], v[192:195], v[28:31]
	v_mfma_f32_16x16x32_bf16 v[24:27], v[142:145], v[192:195], v[24:27]
	v_mfma_f32_16x16x32_bf16 v[12:15], v[134:137], v[204:207], v[12:15]
	v_mfma_f32_16x16x32_bf16 v[8:11], v[142:145], v[204:207], v[8:11]
	v_mfma_f32_16x16x32_bf16 v[52:55], v[156:159], v[172:175], v[52:55]
	v_mfma_f32_16x16x32_bf16 v[48:51], v[164:167], v[172:175], v[48:51]
	v_mfma_f32_16x16x32_bf16 v[36:39], v[156:159], v[180:183], v[36:39]
	v_mfma_f32_16x16x32_bf16 v[32:35], v[164:167], v[180:183], v[32:35]
	v_mfma_f32_16x16x32_bf16 v[20:23], v[156:159], v[188:191], v[20:23]
	v_mfma_f32_16x16x32_bf16 v[16:19], v[164:167], v[188:191], v[16:19]
	v_mfma_f32_16x16x32_bf16 v[4:7], v[156:159], v[196:199], v[4:7]
	v_mfma_f32_16x16x32_bf16 v[0:3], v[164:167], v[196:199], v[0:3]
	v_mfma_f32_16x16x32_bf16 v[52:55], v[160:163], v[176:179], v[52:55]
	v_mfma_f32_16x16x32_bf16 v[48:51], v[168:171], v[176:179], v[48:51]
	v_mfma_f32_16x16x32_bf16 v[36:39], v[160:163], v[184:187], v[36:39]
	v_mfma_f32_16x16x32_bf16 v[32:35], v[168:171], v[184:187], v[32:35]
	v_mfma_f32_16x16x32_bf16 v[20:23], v[160:163], v[192:195], v[20:23]
	v_mfma_f32_16x16x32_bf16 v[16:19], v[168:171], v[192:195], v[16:19]
	v_mfma_f32_16x16x32_bf16 v[4:7], v[160:163], v[204:207], v[4:7]
	v_mfma_f32_16x16x32_bf16 v[0:3], v[168:171], v[204:207], v[0:3]
	s_barrier
	s_add_i32 s84, s84, 2
	s_add_u32 s36, s36, 0x100
	s_addc_u32 s37, s37, 0
	s_cmp_gt_u32 s84, 41
	s_mov_b64 s[96:97], s[42:43]
	s_cbranch_scc0 .LBB0_995
	s_and_b64 vcc, exec, s[62:63]
	s_cbranch_vccz .LBB0_998
	s_barrier
